# v15 + nt hint on the once-read row loads of the LayerNorm / group-norm phases
# speedup vs baseline: 1.0084x; 1.0019x over previous
.LBB0_391:
	global_load_dwordx4 v[0:3], v[12:13], off nt
	global_load_dwordx4 v[4:7], v[12:13], off offset:1024 nt
	global_load_dwordx4 v[8:11], v[12:13], off offset:2048 nt
	global_load_dwordx4 v[24:27], v[12:13], off offset:3072 nt
	v_add_co_u32_e32 v40, vcc, 0xc000000, v12
	v_add_co_u32_e64 v14, s[0:1], s22, v12
	s_nop 0
	v_addc_co_u32_e32 v41, vcc, 0, v13, vcc
	global_load_dwordx4 v[28:31], v[40:41], off nt
	global_load_dwordx4 v[32:35], v[40:41], off offset:1024 nt
	global_load_dwordx4 v[36:39], v[40:41], off offset:2048 nt
	s_nop 0
	global_load_dwordx4 v[40:43], v[40:41], off offset:3072 nt
	v_addc_co_u32_e64 v15, s[0:1], 0, v13, s[0:1]
	s_add_i32 s24, s24, s80
	v_lshl_add_u64 v[12:13], v[12:13], 0, s[20:21]
	s_cmpk_lt_i32 s24, 0x4000
	s_waitcnt vmcnt(7)
	v_lshlrev_b32_e32 v44, 16, v3
	v_and_b32_e32 v45, 0xffff0000, v3
	v_lshlrev_b32_e32 v46, 16, v2
	v_and_b32_e32 v47, 0xffff0000, v2
	v_lshlrev_b32_e32 v2, 16, v1
	v_and_b32_e32 v3, 0xffff0000, v1
	v_lshlrev_b32_e32 v48, 16, v0
	v_and_b32_e32 v49, 0xffff0000, v0
	s_waitcnt vmcnt(6)
	v_lshlrev_b32_e32 v0, 16, v7
	v_and_b32_e32 v1, 0xffff0000, v7
	v_lshlrev_b32_e32 v50, 16, v6
	v_and_b32_e32 v51, 0xffff0000, v6
	v_lshlrev_b32_e32 v6, 16, v5
	v_and_b32_e32 v7, 0xffff0000, v5
	v_lshlrev_b32_e32 v52, 16, v4
	v_and_b32_e32 v53, 0xffff0000, v4
	s_waitcnt vmcnt(5)
	v_lshlrev_b32_e32 v4, 16, v11
	v_and_b32_e32 v5, 0xffff0000, v11
	v_lshlrev_b32_e32 v54, 16, v10
	v_and_b32_e32 v55, 0xffff0000, v10
	v_lshlrev_b32_e32 v10, 16, v9
	v_and_b32_e32 v11, 0xffff0000, v9
	v_lshlrev_b32_e32 v56, 16, v8
	v_and_b32_e32 v57, 0xffff0000, v8
	s_waitcnt vmcnt(4)
	v_lshlrev_b32_e32 v8, 16, v27
	v_and_b32_e32 v9, 0xffff0000, v27
	v_lshlrev_b32_e32 v58, 16, v26
	v_and_b32_e32 v59, 0xffff0000, v26
	v_lshlrev_b32_e32 v26, 16, v25
	v_and_b32_e32 v27, 0xffff0000, v25
	v_lshlrev_b32_e32 v60, 16, v24
	v_and_b32_e32 v61, 0xffff0000, v24
	v_mul_f32_e32 v64, 0xbfb8aa3b, v46
	v_mul_f32_e32 v66, 0xbfb8aa3b, v2
	v_mul_f32_e32 v67, 0xbfb8aa3b, v3
	v_mul_f32_e32 v65, 0xbfb8aa3b, v47
	v_mul_f32_e32 v68, 0xbfb8aa3b, v48
	v_mul_f32_e32 v69, 0xbfb8aa3b, v49
	v_mul_f32_e32 v70, 0xbfb8aa3b, v44
	v_mul_f32_e32 v71, 0xbfb8aa3b, v45
	v_mul_f32_e32 v72, 0xbfb8aa3b, v50
	v_mul_f32_e32 v73, 0xbfb8aa3b, v51
	v_mul_f32_e32 v74, 0xbfb8aa3b, v6
	v_mul_f32_e32 v75, 0xbfb8aa3b, v7
	v_mul_f32_e32 v76, 0xbfb8aa3b, v52
	v_mul_f32_e32 v77, 0xbfb8aa3b, v53
	v_mul_f32_e32 v78, 0xbfb8aa3b, v0
	v_mul_f32_e32 v79, 0xbfb8aa3b, v1
	v_mul_f32_e32 v80, 0xbfb8aa3b, v54
	v_mul_f32_e32 v81, 0xbfb8aa3b, v55
	v_mul_f32_e32 v84, 0xbfb8aa3b, v56
	v_mul_f32_e32 v85, 0xbfb8aa3b, v57
	v_mul_f32_e32 v88, 0xbfb8aa3b, v58
	v_mul_f32_e32 v89, 0xbfb8aa3b, v59
	v_mul_f32_e32 v90, 0xbfb8aa3b, v26
	v_mul_f32_e32 v91, 0xbfb8aa3b, v27
	v_mul_f32_e32 v92, 0xbfb8aa3b, v60
	v_mul_f32_e32 v93, 0xbfb8aa3b, v61
	v_mul_f32_e32 v94, 0xbfb8aa3b, v8
	v_exp_f32_e32 v96, v64
	v_exp_f32_e32 v98, v66
	v_exp_f32_e32 v99, v67
	s_waitcnt vmcnt(3)
	v_lshlrev_b32_e32 v64, 16, v28
	v_mul_f32_e32 v95, 0xbfb8aa3b, v9
	v_lshlrev_b32_e32 v24, 16, v31
	v_and_b32_e32 v25, 0xffff0000, v31
	v_lshlrev_b32_e32 v62, 16, v30
	v_and_b32_e32 v63, 0xffff0000, v30
	v_exp_f32_e32 v97, v65
	v_lshlrev_b32_e32 v30, 16, v29
	v_and_b32_e32 v31, 0xffff0000, v29
	v_and_b32_e32 v65, 0xffff0000, v28
	v_exp_f32_e32 v100, v68
	v_exp_f32_e32 v101, v69
	v_exp_f32_e32 v102, v70
	v_exp_f32_e32 v103, v71
	s_waitcnt vmcnt(2)
	v_lshlrev_b32_e32 v28, 16, v35
	v_and_b32_e32 v29, 0xffff0000, v35
	v_lshlrev_b32_e32 v66, 16, v34
	v_and_b32_e32 v67, 0xffff0000, v34
	v_exp_f32_e32 v104, v72
	v_exp_f32_e32 v105, v73
	v_lshlrev_b32_e32 v34, 16, v33
	v_and_b32_e32 v35, 0xffff0000, v33
	v_exp_f32_e32 v106, v74
	v_exp_f32_e32 v107, v75
	v_lshlrev_b32_e32 v68, 16, v32
	v_and_b32_e32 v69, 0xffff0000, v32
	v_exp_f32_e32 v108, v76
	v_exp_f32_e32 v109, v77
	v_exp_f32_e32 v78, v78
	v_exp_f32_e32 v79, v79
	s_waitcnt vmcnt(1)
	v_lshlrev_b32_e32 v32, 16, v39
	v_and_b32_e32 v33, 0xffff0000, v39
	v_lshlrev_b32_e32 v70, 16, v38
	v_and_b32_e32 v71, 0xffff0000, v38
	v_exp_f32_e32 v80, v80
	v_exp_f32_e32 v81, v81
	v_lshlrev_b32_e32 v38, 16, v37
	v_and_b32_e32 v39, 0xffff0000, v37
	v_lshlrev_b32_e32 v72, 16, v36
	v_and_b32_e32 v73, 0xffff0000, v36
	v_exp_f32_e32 v84, v84
	v_exp_f32_e32 v85, v85
	s_waitcnt vmcnt(0)
	v_lshlrev_b32_e32 v36, 16, v43
	v_and_b32_e32 v37, 0xffff0000, v43
	v_lshlrev_b32_e32 v74, 16, v42
	v_and_b32_e32 v75, 0xffff0000, v42
	v_exp_f32_e32 v88, v88
	v_exp_f32_e32 v89, v89
	v_lshlrev_b32_e32 v42, 16, v41
	v_and_b32_e32 v43, 0xffff0000, v41
	v_exp_f32_e32 v41, v90
	v_exp_f32_e32 v90, v91
	v_lshlrev_b32_e32 v76, 16, v40
	v_and_b32_e32 v77, 0xffff0000, v40
	v_exp_f32_e32 v40, v92
	v_exp_f32_e32 v91, v93
	v_exp_f32_e32 v92, v94
	v_add_f32_e32 v94, 0, v64
	v_exp_f32_e32 v93, v95
	v_add_f32_e32 v95, 0, v68
	v_add_f32_e32 v110, 0, v72
	v_add_f32_e32 v111, 0, v76
	v_add_f32_e32 v94, v94, v65
	v_add_f32_e32 v95, v95, v69
	v_add_f32_e32 v110, v110, v73
	v_add_f32_e32 v111, v111, v77
	v_add_f32_e32 v94, v94, v30
	v_add_f32_e32 v95, v95, v34
	v_add_f32_e32 v110, v110, v38
	v_add_f32_e32 v111, v111, v42
	v_add_f32_e32 v98, 1.0, v98
	v_add_f32_e32 v99, 1.0, v99
	v_add_f32_e32 v94, v94, v31
	v_add_f32_e32 v96, 1.0, v96
	v_add_f32_e32 v97, 1.0, v97
	v_add_f32_e32 v100, 1.0, v100
	v_add_f32_e32 v101, 1.0, v101
	v_add_f32_e32 v104, 1.0, v104
	v_add_f32_e32 v105, 1.0, v105
	v_add_f32_e32 v108, 1.0, v108
	v_add_f32_e32 v109, 1.0, v109
	v_add_f32_e32 v95, v95, v35
	v_add_f32_e32 v112, 1.0, v78
	v_add_f32_e32 v113, 1.0, v79
	v_add_f32_e32 v114, 1.0, v80
	v_add_f32_e32 v115, 1.0, v81
	v_add_f32_e32 v118, 1.0, v84
	v_add_f32_e32 v119, 1.0, v85
	v_add_f32_e32 v110, v110, v39
	v_add_f32_e32 v122, 1.0, v88
	v_add_f32_e32 v123, 1.0, v89
	v_add_f32_e32 v126, 1.0, v40
	v_add_f32_e32 v127, 1.0, v91
	v_add_f32_e32 v111, v111, v43
	v_rcp_f32_e32 v78, v98
	v_rcp_f32_e32 v79, v99
	v_add_f32_e32 v130, v94, v62
	v_add_f32_e32 v124, 1.0, v41
	v_add_f32_e32 v128, 1.0, v92
	v_add_f32_e32 v129, 1.0, v93
	v_rcp_f32_e32 v40, v96
	v_rcp_f32_e32 v41, v97
	v_rcp_f32_e32 v80, v100
	v_rcp_f32_e32 v81, v101
	v_rcp_f32_e32 v84, v104
	v_rcp_f32_e32 v85, v105
	v_rcp_f32_e32 v88, v108
	v_rcp_f32_e32 v89, v109
	v_add_f32_e32 v108, v95, v66
	v_rcp_f32_e32 v92, v114
	v_rcp_f32_e32 v93, v115
	v_rcp_f32_e32 v96, v118
	v_rcp_f32_e32 v97, v119
	v_add_f32_e32 v109, v110, v70
	v_rcp_f32_e32 v100, v122
	v_rcp_f32_e32 v101, v123
	v_rcp_f32_e32 v104, v126
	v_rcp_f32_e32 v105, v127
	v_add_f32_e32 v110, v111, v74
	v_add_f32_e32 v111, v130, v63
	v_mul_f32_e32 v82, 0xbfb8aa3b, v10
	v_mul_f32_e32 v83, 0xbfb8aa3b, v11
	v_add_f32_e32 v108, v108, v67
	v_add_f32_e32 v109, v109, v71
	v_add_f32_e32 v110, v110, v75
	v_add_f32_e32 v111, v111, v24
	v_exp_f32_e32 v82, v82
	v_exp_f32_e32 v83, v83
	v_add_f32_e32 v108, v108, v28
	v_add_f32_e32 v109, v109, v32
	v_add_f32_e32 v110, v110, v36
	v_add_f32_e32 v111, v111, v25
	v_add_f32_e32 v108, v108, v29
	v_add_f32_e32 v109, v109, v33
	v_add_f32_e32 v110, v110, v37
	v_pk_mul_f32 v[2:3], v[78:79], v[2:3]
	ds_bpermute_b32 v78, v16, v111
	v_pk_mul_f32 v[40:41], v[40:41], v[46:47]
	v_pk_mul_f32 v[46:47], v[80:81], v[48:49]
	v_pk_mul_f32 v[48:49], v[84:85], v[50:51]
	v_pk_mul_f32 v[50:51], v[88:89], v[52:53]
	ds_bpermute_b32 v79, v16, v108
	v_pk_mul_f32 v[52:53], v[92:93], v[54:55]
	v_pk_mul_f32 v[54:55], v[96:97], v[56:57]
	ds_bpermute_b32 v80, v16, v109
	v_pk_mul_f32 v[56:57], v[100:101], v[58:59]
	v_pk_mul_f32 v[58:59], v[104:105], v[60:61]
	ds_bpermute_b32 v60, v16, v110
	v_add_f32_e32 v102, 1.0, v102
	v_add_f32_e32 v103, 1.0, v103
	v_add_f32_e32 v116, 1.0, v82
	v_add_f32_e32 v117, 1.0, v83
	v_rcp_f32_e32 v82, v102
	v_rcp_f32_e32 v83, v103
	s_waitcnt lgkmcnt(3)
	v_add_f32_e32 v61, v111, v78
	s_waitcnt lgkmcnt(2)
	v_add_f32_e32 v78, v108, v79
	s_waitcnt lgkmcnt(1)
	v_add_f32_e32 v79, v109, v80
	s_waitcnt lgkmcnt(0)
	v_add_f32_e32 v60, v110, v60
	ds_bpermute_b32 v80, v17, v61
	v_pk_mul_f32 v[44:45], v[82:83], v[44:45]
	ds_bpermute_b32 v81, v17, v78
	ds_bpermute_b32 v82, v17, v79
	ds_bpermute_b32 v83, v17, v60
	s_waitcnt lgkmcnt(3)
	v_add_f32_e32 v61, v61, v80
	ds_bpermute_b32 v80, v18, v61
	s_waitcnt lgkmcnt(3)
	v_add_f32_e32 v78, v78, v81
	s_waitcnt lgkmcnt(2)
	v_add_f32_e32 v79, v79, v82
	s_waitcnt lgkmcnt(1)
	v_add_f32_e32 v60, v60, v83
	ds_bpermute_b32 v81, v18, v78
	ds_bpermute_b32 v82, v18, v79
	ds_bpermute_b32 v83, v18, v60
	s_waitcnt lgkmcnt(3)
	v_add_f32_e32 v61, v61, v80
	ds_bpermute_b32 v80, v19, v61
	s_waitcnt lgkmcnt(3)
	v_add_f32_e32 v78, v78, v81
	s_waitcnt lgkmcnt(2)
	v_add_f32_e32 v79, v79, v82
	s_waitcnt lgkmcnt(1)
	v_add_f32_e32 v60, v60, v83
	ds_bpermute_b32 v81, v19, v78
	ds_bpermute_b32 v82, v19, v79
	ds_bpermute_b32 v83, v19, v60
	s_waitcnt lgkmcnt(3)
	v_add_f32_e32 v61, v61, v80
	ds_bpermute_b32 v80, v20, v61
	s_waitcnt lgkmcnt(3)
	v_add_f32_e32 v78, v78, v81
	s_waitcnt lgkmcnt(2)
	v_add_f32_e32 v79, v79, v82
	s_waitcnt lgkmcnt(1)
	v_add_f32_e32 v60, v60, v83
	ds_bpermute_b32 v81, v20, v78
	ds_bpermute_b32 v82, v20, v79
	ds_bpermute_b32 v83, v20, v60
	v_mul_f32_e32 v86, 0xbfb8aa3b, v4
	v_mul_f32_e32 v87, 0xbfb8aa3b, v5
	v_exp_f32_e32 v86, v86
	v_exp_f32_e32 v87, v87
	s_waitcnt lgkmcnt(3)
	v_add_f32_e32 v61, v61, v80
	s_waitcnt lgkmcnt(2)
	v_add_f32_e32 v78, v78, v81
	s_waitcnt lgkmcnt(1)
	v_add_f32_e32 v79, v79, v82
	s_waitcnt lgkmcnt(0)
	v_add_f32_e32 v60, v60, v83
	ds_bpermute_b32 v80, v21, v61
	ds_bpermute_b32 v81, v21, v78
	ds_bpermute_b32 v82, v21, v79
	ds_bpermute_b32 v83, v21, v60
	v_add_f32_e32 v106, 1.0, v106
	v_add_f32_e32 v107, 1.0, v107
	v_add_f32_e32 v120, 1.0, v86
	v_add_f32_e32 v121, 1.0, v87
	v_add_f32_e32 v125, 1.0, v90
	v_rcp_f32_e32 v86, v106
	v_rcp_f32_e32 v87, v107
	v_rcp_f32_e32 v90, v112
	v_rcp_f32_e32 v91, v113
	v_rcp_f32_e32 v94, v116
	v_rcp_f32_e32 v95, v117
	v_rcp_f32_e32 v98, v120
	v_rcp_f32_e32 v99, v121
	v_rcp_f32_e32 v106, v128
	v_rcp_f32_e32 v107, v129
	s_waitcnt lgkmcnt(3)
	v_add_f32_e32 v61, v61, v80
	s_waitcnt lgkmcnt(2)
	v_add_f32_e32 v78, v78, v81
	s_waitcnt lgkmcnt(1)
	v_add_f32_e32 v79, v79, v82
	s_waitcnt lgkmcnt(0)
	v_add_f32_e32 v81, v60, v83
	v_mul_f32_e32 v60, 0x3b000000, v61
	v_mul_f32_e32 v78, 0x3b000000, v78
	v_mul_f32_e32 v80, 0x3b000000, v79
	v_mul_f32_e32 v82, 0x3b000000, v81
	v_pk_add_f32 v[64:65], v[64:65], v[60:61] op_sel_hi:[1,0] neg_lo:[0,1] neg_hi:[0,1]
	v_pk_mul_f32 v[6:7], v[86:87], v[6:7]
	v_pk_mul_f32 v[0:1], v[90:91], v[0:1]
	v_pk_mul_f32 v[10:11], v[94:95], v[10:11]
	v_pk_mul_f32 v[4:5], v[98:99], v[4:5]
	v_pk_mul_f32 v[8:9], v[106:107], v[8:9]
	v_pk_add_f32 v[30:31], v[30:31], v[60:61] op_sel_hi:[1,0] neg_lo:[0,1] neg_hi:[0,1]
	v_pk_add_f32 v[62:63], v[62:63], v[60:61] op_sel_hi:[1,0] neg_lo:[0,1] neg_hi:[0,1]
	v_pk_add_f32 v[24:25], v[24:25], v[60:61] op_sel_hi:[1,0] neg_lo:[0,1] neg_hi:[0,1]
	v_pk_add_f32 v[60:61], v[68:69], v[78:79] op_sel_hi:[1,0] neg_lo:[0,1] neg_hi:[0,1]
	v_pk_add_f32 v[34:35], v[34:35], v[78:79] op_sel_hi:[1,0] neg_lo:[0,1] neg_hi:[0,1]
	v_pk_add_f32 v[66:67], v[66:67], v[78:79] op_sel_hi:[1,0] neg_lo:[0,1] neg_hi:[0,1]
	v_pk_add_f32 v[28:29], v[28:29], v[78:79] op_sel_hi:[1,0] neg_lo:[0,1] neg_hi:[0,1]
	v_pk_add_f32 v[68:69], v[72:73], v[80:81] op_sel_hi:[1,0] neg_lo:[0,1] neg_hi:[0,1]
	v_pk_add_f32 v[38:39], v[38:39], v[80:81] op_sel_hi:[1,0] neg_lo:[0,1] neg_hi:[0,1]
	v_pk_add_f32 v[70:71], v[70:71], v[80:81] op_sel_hi:[1,0] neg_lo:[0,1] neg_hi:[0,1]
	v_pk_add_f32 v[32:33], v[32:33], v[80:81] op_sel_hi:[1,0] neg_lo:[0,1] neg_hi:[0,1]
	v_pk_add_f32 v[72:73], v[76:77], v[82:83] op_sel_hi:[1,0] neg_lo:[0,1] neg_hi:[0,1]
	v_pk_add_f32 v[36:37], v[36:37], v[82:83] op_sel_hi:[1,0] neg_lo:[0,1] neg_hi:[0,1]
	v_pk_mul_f32 v[76:77], v[64:65], v[64:65]
	v_pk_add_f32 v[42:43], v[42:43], v[82:83] op_sel_hi:[1,0] neg_lo:[0,1] neg_hi:[0,1]
	v_pk_add_f32 v[74:75], v[74:75], v[82:83] op_sel_hi:[1,0] neg_lo:[0,1] neg_hi:[0,1]
	v_pk_mul_f32 v[78:79], v[30:31], v[30:31]
	v_pk_mul_f32 v[80:81], v[62:63], v[62:63]
	v_pk_mul_f32 v[82:83], v[24:25], v[24:25]
	v_pk_mul_f32 v[46:47], v[46:47], v[64:65]
	v_pk_mul_f32 v[2:3], v[2:3], v[30:31]
	v_pk_mul_f32 v[30:31], v[40:41], v[62:63]
	v_pk_mul_f32 v[24:25], v[44:45], v[24:25]
	v_pk_mul_f32 v[40:41], v[60:61], v[60:61]
	v_pk_mul_f32 v[44:45], v[34:35], v[34:35]
	v_pk_mul_f32 v[62:63], v[66:67], v[66:67]
	v_pk_mul_f32 v[64:65], v[28:29], v[28:29]
	v_pk_mul_f32 v[50:51], v[50:51], v[60:61]
	v_pk_mul_f32 v[6:7], v[6:7], v[34:35]
	v_pk_mul_f32 v[34:35], v[48:49], v[66:67]
	v_pk_mul_f32 v[28:29], v[0:1], v[28:29]
	v_pk_mul_f32 v[0:1], v[68:69], v[68:69]
	v_pk_mul_f32 v[48:49], v[38:39], v[38:39]
	v_pk_mul_f32 v[60:61], v[70:71], v[70:71]
	v_pk_mul_f32 v[66:67], v[32:33], v[32:33]
	v_pk_mul_f32 v[10:11], v[10:11], v[38:39]
	v_pk_mul_f32 v[38:39], v[52:53], v[70:71]
	v_pk_mul_f32 v[4:5], v[4:5], v[32:33]
	v_pk_mul_f32 v[32:33], v[72:73], v[72:73]
	v_pk_mul_f32 v[70:71], v[36:37], v[36:37]
	v_pk_mul_f32 v[8:9], v[8:9], v[36:37]
	v_add_f32_e32 v36, v76, v77
	v_add_f32_e32 v37, v40, v41
	v_add_f32_e32 v0, v0, v1
	v_add_f32_e32 v1, v32, v33
	v_add_f32_e32 v32, v78, v36
	v_add_f32_e32 v33, v44, v37
	v_add_f32_e32 v0, v48, v0
	v_add_f32_e32 v32, v79, v32
	v_pk_mul_f32 v[52:53], v[42:43], v[42:43]
	v_add_f32_e32 v33, v45, v33
	v_add_f32_e32 v0, v49, v0
	v_add_f32_e32 v32, v80, v32
	v_add_f32_e32 v1, v52, v1
	v_add_f32_e32 v33, v62, v33
	v_add_f32_e32 v0, v60, v0
	v_add_f32_e32 v32, v81, v32
	v_pk_mul_f32 v[54:55], v[54:55], v[68:69]
	v_pk_mul_f32 v[68:69], v[74:75], v[74:75]
	v_add_f32_e32 v1, v53, v1
	v_add_f32_e32 v33, v63, v33
	v_add_f32_e32 v0, v61, v0
	v_add_f32_e32 v32, v82, v32
	v_add_f32_e32 v1, v68, v1
	v_add_f32_e32 v33, v64, v33
	v_add_f32_e32 v0, v66, v0
	v_add_f32_e32 v32, v83, v32
	v_add_f32_e32 v1, v69, v1
	v_add_f32_e32 v33, v65, v33
	v_add_f32_e32 v0, v67, v0
	ds_bpermute_b32 v36, v16, v32
	v_add_f32_e32 v1, v70, v1
	ds_bpermute_b32 v37, v16, v33
	ds_bpermute_b32 v40, v16, v0
	v_add_f32_e32 v1, v71, v1
	ds_bpermute_b32 v41, v16, v1
	s_waitcnt lgkmcnt(3)
	v_add_f32_e32 v32, v32, v36
	s_waitcnt lgkmcnt(2)
	v_add_f32_e32 v33, v33, v37
	s_waitcnt lgkmcnt(1)
	v_add_f32_e32 v0, v0, v40
	ds_bpermute_b32 v36, v17, v32
	ds_bpermute_b32 v37, v17, v33
	ds_bpermute_b32 v40, v17, v0
	s_waitcnt lgkmcnt(3)
	v_add_f32_e32 v1, v1, v41
	ds_bpermute_b32 v41, v17, v1
	s_waitcnt lgkmcnt(3)
	v_add_f32_e32 v32, v32, v36
	s_waitcnt lgkmcnt(2)
	v_add_f32_e32 v33, v33, v37
	s_waitcnt lgkmcnt(1)
	v_add_f32_e32 v0, v0, v40
	ds_bpermute_b32 v36, v18, v32
	ds_bpermute_b32 v37, v18, v33
	ds_bpermute_b32 v40, v18, v0
	s_waitcnt lgkmcnt(3)
	v_add_f32_e32 v1, v1, v41
	ds_bpermute_b32 v41, v18, v1
	s_waitcnt lgkmcnt(3)
	v_add_f32_e32 v32, v32, v36
	s_waitcnt lgkmcnt(2)
	v_add_f32_e32 v33, v33, v37
	s_waitcnt lgkmcnt(1)
	v_add_f32_e32 v0, v0, v40
	ds_bpermute_b32 v36, v19, v32
	ds_bpermute_b32 v37, v19, v33
	ds_bpermute_b32 v40, v19, v0
	s_waitcnt lgkmcnt(3)
	v_add_f32_e32 v1, v1, v41
	ds_bpermute_b32 v41, v19, v1
	s_waitcnt lgkmcnt(3)
	v_add_f32_e32 v32, v32, v36
	s_waitcnt lgkmcnt(2)
	v_add_f32_e32 v33, v33, v37
	s_waitcnt lgkmcnt(1)
	v_add_f32_e32 v0, v0, v40
	ds_bpermute_b32 v36, v20, v32
	ds_bpermute_b32 v37, v20, v33
	ds_bpermute_b32 v40, v20, v0
	s_waitcnt lgkmcnt(3)
	v_add_f32_e32 v1, v1, v41
	ds_bpermute_b32 v41, v20, v1
	s_waitcnt lgkmcnt(3)
	v_add_f32_e32 v32, v32, v36
	s_waitcnt lgkmcnt(2)
	v_add_f32_e32 v33, v33, v37
	s_waitcnt lgkmcnt(1)
	v_add_f32_e32 v0, v0, v40
	ds_bpermute_b32 v36, v21, v32
	ds_bpermute_b32 v37, v21, v33
	ds_bpermute_b32 v40, v21, v0
	s_waitcnt lgkmcnt(3)
	v_add_f32_e32 v1, v1, v41
	ds_bpermute_b32 v41, v21, v1
	s_waitcnt lgkmcnt(3)
	v_add_f32_e32 v32, v32, v36
	s_waitcnt lgkmcnt(2)
	v_add_f32_e32 v33, v33, v37
	s_waitcnt lgkmcnt(1)
	v_add_f32_e32 v0, v0, v40
	v_fmamk_f32 v32, v32, 0x3b000000, v22
	v_fmamk_f32 v33, v33, 0x3b000000, v22
	v_fmamk_f32 v0, v0, 0x3b000000, v22
	v_mul_f32_e32 v36, 0x4f800000, v32
	v_cmp_gt_f32_e64 s[6:7], s3, v32
	s_waitcnt lgkmcnt(0)
	v_add_f32_e32 v1, v1, v41
	v_mul_f32_e32 v37, 0x4f800000, v33
	v_cmp_gt_f32_e32 vcc, s3, v33
	v_mul_f32_e32 v40, 0x4f800000, v0
	v_cmp_gt_f32_e64 s[0:1], s3, v0
	v_cndmask_b32_e64 v32, v32, v36, s[6:7]
	v_fmamk_f32 v1, v1, 0x3b000000, v22
	v_cndmask_b32_e32 v33, v33, v37, vcc
	v_cndmask_b32_e64 v0, v0, v40, s[0:1]
	v_sqrt_f32_e32 v36, v32
	v_mul_f32_e32 v41, 0x4f800000, v1
	v_cmp_gt_f32_e64 s[4:5], s3, v1
	v_sqrt_f32_e32 v37, v33
	v_sqrt_f32_e32 v40, v0
	v_rcp_f32_e32 v102, v124
	v_rcp_f32_e32 v103, v125
	v_cndmask_b32_e64 v1, v1, v41, s[4:5]
	v_sqrt_f32_e32 v41, v1
	v_add_u32_e32 v44, -1, v36
	v_add_u32_e32 v45, 1, v36
	v_add_u32_e32 v48, -1, v37
	v_add_u32_e32 v52, -1, v40
	v_fma_f32 v60, -v44, v36, v32
	v_pk_mul_f32 v[26:27], v[102:103], v[26:27]
	v_add_u32_e32 v49, 1, v37
	v_add_u32_e32 v53, 1, v40
	v_fma_f32 v61, -v45, v36, v32
	v_fma_f32 v62, -v48, v37, v33
	v_fma_f32 v64, -v52, v40, v0
	v_cmp_ge_f32_e64 s[8:9], 0, v60
	v_pk_mul_f32 v[26:27], v[26:27], v[42:43]
	v_pk_mul_f32 v[42:43], v[56:57], v[74:75]
	v_add_u32_e32 v56, -1, v41
	v_fma_f32 v63, -v49, v37, v33
	v_fma_f32 v65, -v53, v40, v0
	v_cndmask_b32_e64 v36, v36, v44, s[8:9]
	v_cmp_ge_f32_e64 s[8:9], 0, v62
	v_cmp_ge_f32_e64 s[10:11], 0, v64
	v_cmp_lt_f32_e64 s[14:15], 0, v61
	v_add_u32_e32 v57, 1, v41
	v_fma_f32 v66, -v56, v41, v1
	v_cndmask_b32_e64 v37, v37, v48, s[8:9]
	v_cmp_lt_f32_e64 s[8:9], 0, v63
	v_cndmask_b32_e64 v40, v40, v52, s[10:11]
	v_cmp_lt_f32_e64 s[10:11], 0, v65
	v_cndmask_b32_e64 v36, v36, v45, s[14:15]
	v_fma_f32 v67, -v57, v41, v1
	v_cmp_ge_f32_e64 s[12:13], 0, v66
	v_cndmask_b32_e64 v37, v37, v49, s[8:9]
	v_cndmask_b32_e64 v40, v40, v53, s[10:11]
	v_mul_f32_e32 v44, 0x37800000, v36
	v_cndmask_b32_e64 v41, v41, v56, s[12:13]
	v_cmp_lt_f32_e64 s[12:13], 0, v67
	v_mul_f32_e32 v45, 0x37800000, v37
	v_mul_f32_e32 v48, 0x37800000, v40
	v_cndmask_b32_e64 v36, v36, v44, s[6:7]
	v_cmp_class_f32_e64 s[6:7], v32, v23
	v_cndmask_b32_e64 v41, v41, v57, s[12:13]
	v_cndmask_b32_e32 v37, v37, v45, vcc
	v_cmp_class_f32_e32 vcc, v33, v23
	v_cndmask_b32_e64 v40, v40, v48, s[0:1]
	v_cmp_class_f32_e64 s[0:1], v0, v23
	v_cndmask_b32_e64 v32, v36, v32, s[6:7]
	v_mul_f32_e32 v49, 0x37800000, v41
	v_cndmask_b32_e32 v36, v37, v33, vcc
	v_cndmask_b32_e64 v37, v40, v0, s[0:1]
	v_div_scale_f32 v0, s[0:1], v32, v32, 1.0
	v_cndmask_b32_e64 v41, v41, v49, s[4:5]
	v_cmp_class_f32_e64 s[4:5], v1, v23
	v_div_scale_f32 v33, s[0:1], v36, v36, 1.0
	v_rcp_f32_e32 v52, v0
	v_cndmask_b32_e64 v40, v41, v1, s[4:5]
	v_div_scale_f32 v44, s[4:5], v37, v37, 1.0
	v_rcp_f32_e32 v53, v33
	v_div_scale_f32 v48, s[6:7], v40, v40, 1.0
	v_rcp_f32_e32 v56, v44
	v_rcp_f32_e32 v57, v48
	v_fma_f32 v60, -v0, v52, 1.0
	v_div_scale_f32 v1, vcc, 1.0, v32, 1.0
	v_fma_f32 v61, -v33, v53, 1.0
	v_fmac_f32_e32 v52, v60, v52
	v_div_scale_f32 v41, s[0:1], 1.0, v36, 1.0
	v_fma_f32 v62, -v44, v56, 1.0
	v_fmac_f32_e32 v53, v61, v53
	v_mul_f32_e32 v60, v1, v52
	v_div_scale_f32 v45, s[4:5], 1.0, v37, 1.0
	v_fma_f32 v63, -v48, v57, 1.0
	v_fmac_f32_e32 v56, v62, v56
	v_mul_f32_e32 v61, v41, v53
	v_fma_f32 v64, -v0, v60, v1
	v_div_scale_f32 v49, s[6:7], 1.0, v40, 1.0
	v_fmac_f32_e32 v57, v63, v57
	v_mul_f32_e32 v62, v45, v56
	v_fma_f32 v65, -v33, v61, v41
	v_fmac_f32_e32 v60, v64, v52
	v_mul_f32_e32 v63, v49, v57
	v_fma_f32 v66, -v44, v62, v45
	v_fmac_f32_e32 v61, v65, v53
	v_fma_f32 v0, -v0, v60, v1
	v_fma_f32 v67, -v48, v63, v49
	v_fmac_f32_e32 v62, v66, v56
	v_fma_f32 v1, -v33, v61, v41
	v_div_fmas_f32 v0, v0, v52, v60
	s_mov_b64 vcc, s[0:1]
	v_fmac_f32_e32 v63, v67, v57
	v_fma_f32 v41, -v44, v62, v45
	v_div_fixup_f32 v0, v0, v32, 1.0
	v_div_fmas_f32 v1, v1, v53, v61
	s_mov_b64 vcc, s[4:5]
	v_fma_f32 v44, -v48, v63, v49
	v_pk_mul_f32 v[32:33], v[46:47], v[0:1] op_sel_hi:[1,0]
	v_pk_mul_f32 v[2:3], v[2:3], v[0:1] op_sel_hi:[1,0]
	v_pk_mul_f32 v[30:31], v[30:31], v[0:1] op_sel_hi:[1,0]
	v_pk_mul_f32 v[24:25], v[24:25], v[0:1] op_sel_hi:[1,0]
	v_div_fixup_f32 v36, v1, v36, 1.0
	v_div_fmas_f32 v41, v41, v56, v62
	s_mov_b64 vcc, s[6:7]
	v_cvt_pk_bf16_f32 v0, v32, v33
	v_cvt_pk_bf16_f32 v1, v2, v3
	v_cvt_pk_bf16_f32 v2, v30, v31
	v_cvt_pk_bf16_f32 v3, v24, v25
	v_pk_mul_f32 v[24:25], v[50:51], v[36:37] op_sel_hi:[1,0]
	v_pk_mul_f32 v[6:7], v[6:7], v[36:37] op_sel_hi:[1,0]
	v_pk_mul_f32 v[30:31], v[34:35], v[36:37] op_sel_hi:[1,0]
	v_pk_mul_f32 v[28:29], v[28:29], v[36:37] op_sel_hi:[1,0]
	v_div_fixup_f32 v32, v41, v37, 1.0
	v_div_fmas_f32 v33, v44, v57, v63
	v_pk_mul_f32 v[58:59], v[58:59], v[72:73]
	global_store_dwordx4 v[14:15], v[0:3], off
	v_pk_mul_f32 v[10:11], v[10:11], v[32:33] op_sel_hi:[1,0]
	v_pk_mul_f32 v[4:5], v[4:5], v[32:33] op_sel_hi:[1,0]
	v_cvt_pk_bf16_f32 v0, v24, v25
	v_cvt_pk_bf16_f32 v1, v6, v7
	v_cvt_pk_bf16_f32 v2, v30, v31
	v_cvt_pk_bf16_f32 v3, v28, v29
	v_pk_mul_f32 v[6:7], v[54:55], v[32:33] op_sel_hi:[1,0]
	v_pk_mul_f32 v[24:25], v[38:39], v[32:33] op_sel_hi:[1,0]
	v_div_fixup_f32 v28, v33, v40, 1.0
	global_store_dwordx4 v[14:15], v[0:3], off offset:1024
	v_pk_mul_f32 v[8:9], v[8:9], v[28:29] op_sel_hi:[1,0]
	s_nop 0
	v_cvt_pk_bf16_f32 v0, v6, v7
	v_cvt_pk_bf16_f32 v1, v10, v11
	v_cvt_pk_bf16_f32 v2, v24, v25
	v_cvt_pk_bf16_f32 v3, v4, v5
	v_pk_mul_f32 v[4:5], v[58:59], v[28:29] op_sel_hi:[1,0]
	v_pk_mul_f32 v[6:7], v[26:27], v[28:29] op_sel_hi:[1,0]
	v_pk_mul_f32 v[10:11], v[42:43], v[28:29] op_sel_hi:[1,0]
	global_store_dwordx4 v[14:15], v[0:3], off offset:2048
	s_nop 1
	v_cvt_pk_bf16_f32 v0, v4, v5
	v_cvt_pk_bf16_f32 v1, v6, v7
	v_cvt_pk_bf16_f32 v2, v10, v11
	v_cvt_pk_bf16_f32 v3, v8, v9
	global_store_dwordx4 v[14:15], v[0:3], off offset:3072
	s_cbranch_scc1 .LBB0_391
	v_readlane_b32 s81, v234, 49

.LBB0_521:
	v_lshl_add_u64 v[46:47], s[84:85], 0, v[8:9]
	v_lshl_add_u64 v[10:11], s[16:17], 0, v[6:7]
	v_lshl_add_u64 v[48:49], s[84:85], 0, v[6:7]
	v_add_co_u32_e32 v46, vcc, 0x14400000, v46
	global_load_dwordx4 v[22:25], v[0:1], off
	global_load_dwordx4 v[26:29], v[2:3], off
	global_load_dwordx4 v[30:33], v[10:11], off nt
	global_load_dwordx4 v[34:37], v[10:11], off offset:1024 nt
	global_load_dwordx4 v[38:41], v[10:11], off offset:2048 nt
	global_load_dwordx4 v[42:45], v[10:11], off offset:3072 nt
	v_add_co_u32_e64 v10, s[0:1], s11, v48
	v_addc_co_u32_e32 v47, vcc, 0, v47, vcc
	s_nop 0
	v_addc_co_u32_e64 v11, s[0:1], 0, v49, s[0:1]
	global_load_dwordx2 v[48:49], v[46:47], off nt
	global_load_dwordx2 v[50:51], v[46:47], off offset:512 nt
	global_load_dwordx2 v[52:53], v[46:47], off offset:1024 nt
	s_nop 0
	global_load_dwordx2 v[46:47], v[46:47], off offset:1536 nt
	s_add_i32 s14, s14, s80
	v_lshl_add_u64 v[6:7], v[6:7], 0, s[6:7]
	v_lshl_add_u64 v[8:9], v[8:9], 0, s[8:9]
	s_cmpk_lt_i32 s14, 0x4000
	s_waitcnt vmcnt(3)
	v_lshlrev_b32_e32 v54, 16, v48
	v_and_b32_e32 v55, 0xffff0000, v48
	v_lshlrev_b32_e32 v48, 16, v49
	v_and_b32_e32 v49, 0xffff0000, v49
	s_waitcnt vmcnt(2)
	v_lshlrev_b32_e32 v56, 16, v50
	v_and_b32_e32 v57, 0xffff0000, v50
	v_lshlrev_b32_e32 v50, 16, v51
	v_and_b32_e32 v51, 0xffff0000, v51
	s_waitcnt vmcnt(1)
	v_lshlrev_b32_e32 v58, 16, v52
	v_and_b32_e32 v59, 0xffff0000, v52
	v_lshlrev_b32_e32 v52, 16, v53
	v_and_b32_e32 v53, 0xffff0000, v53
	s_waitcnt vmcnt(0)
	v_lshlrev_b32_e32 v60, 16, v46
	v_and_b32_e32 v61, 0xffff0000, v46
	v_lshlrev_b32_e32 v46, 16, v47
	v_and_b32_e32 v47, 0xffff0000, v47
	v_pk_fma_f32 v[32:33], v[32:33], s[10:11], v[48:49] op_sel_hi:[1,0,1]
	v_pk_fma_f32 v[30:31], v[30:31], s[10:11], v[54:55] op_sel_hi:[1,0,1]
	v_pk_fma_f32 v[36:37], v[36:37], s[10:11], v[50:51] op_sel_hi:[1,0,1]
	v_pk_fma_f32 v[34:35], v[34:35], s[10:11], v[56:57] op_sel_hi:[1,0,1]
	v_pk_fma_f32 v[40:41], v[40:41], s[10:11], v[52:53] op_sel_hi:[1,0,1]
	v_pk_fma_f32 v[44:45], v[44:45], s[10:11], v[46:47] op_sel_hi:[1,0,1]
	v_pk_mov_b32 v[46:47], v[30:31], v[32:33] op_sel:[1,0]
	v_mov_b32_e32 v48, v30
	v_mov_b32_e32 v49, v33
	v_pk_mov_b32 v[50:51], v[34:35], v[36:37] op_sel:[1,0]
	v_mov_b32_e32 v52, v34
	v_mov_b32_e32 v53, v37
	v_pk_add_f32 v[46:47], v[46:47], v[48:49]
	v_pk_add_f32 v[48:49], v[50:51], v[52:53]
	v_pk_fma_f32 v[38:39], v[38:39], s[10:11], v[58:59] op_sel_hi:[1,0,1]
	v_pk_fma_f32 v[42:43], v[42:43], s[10:11], v[60:61] op_sel_hi:[1,0,1]
	v_add_f32_e32 v21, v46, v47
	v_pk_add_f32 v[46:47], v[48:49], v[48:49] op_sel:[0,1] op_sel_hi:[1,0]
	v_add_f32_e32 v54, v38, v39
	v_add_f32_e32 v56, v40, v41
	v_mov_b32_e32 v59, v42
	v_mov_b32_e32 v55, v44
	v_mov_b32_e32 v57, v45
	v_add_f32_e32 v58, 0, v21
	v_mov_b32_e32 v47, v43
	v_pk_add_f32 v[50:51], v[54:55], v[56:57]
	v_pk_add_f32 v[46:47], v[58:59], v[46:47]
	s_nop 0
	v_pk_add_f32 v[46:47], v[46:47], v[50:51]
	s_nop 0
	v_add_f32_e32 v21, v46, v47
	ds_bpermute_b32 v46, v12, v21
	s_waitcnt lgkmcnt(0)
	v_add_f32_e32 v21, v21, v46
	ds_bpermute_b32 v46, v13, v21
	s_waitcnt lgkmcnt(0)
	v_add_f32_e32 v21, v21, v46
	ds_bpermute_b32 v46, v14, v21
	s_waitcnt lgkmcnt(0)
	v_add_f32_e32 v21, v21, v46
	ds_bpermute_b32 v46, v15, v21
	s_waitcnt lgkmcnt(0)
	v_add_f32_e32 v21, v21, v46
	ds_bpermute_b32 v46, v16, v21
	s_waitcnt lgkmcnt(0)
	v_add_f32_e32 v21, v21, v46
	ds_bpermute_b32 v46, v17, v21
	s_waitcnt lgkmcnt(0)
	v_add_f32_e32 v21, v21, v46
	v_fmamk_f32 v31, v21, 0xba800000, v31
	v_fmac_f32_e32 v30, 0xba800000, v21
	v_fmamk_f32 v33, v21, 0xba800000, v33
	v_fmac_f32_e32 v32, 0xba800000, v21
	v_fmamk_f32 v35, v21, 0xba800000, v35
	v_fmac_f32_e32 v34, 0xba800000, v21
	v_fmamk_f32 v37, v21, 0xba800000, v37
	v_fmac_f32_e32 v36, 0xba800000, v21
	v_pk_mul_f32 v[46:47], v[32:33], v[32:33]
	v_pk_mul_f32 v[48:49], v[30:31], v[30:31]
	v_pk_mul_f32 v[50:51], v[36:37], v[36:37]
	v_pk_mul_f32 v[52:53], v[34:35], v[34:35]
	v_fmac_f32_e32 v38, 0xba800000, v21
	v_fmac_f32_e32 v40, 0xba800000, v21
	v_pk_mov_b32 v[58:59], v[48:49], v[46:47] op_sel:[1,0]
	v_mov_b32_e32 v49, v47
	v_pk_mov_b32 v[46:47], v[52:53], v[50:51] op_sel:[1,0]
	v_mov_b32_e32 v53, v51
	v_fmamk_f32 v39, v21, 0xba800000, v39
	v_fmamk_f32 v41, v21, 0xba800000, v41
	v_mul_f32_e32 v54, v38, v38
	v_mul_f32_e32 v56, v40, v40
	v_pk_add_f32 v[48:49], v[58:59], v[48:49]
	v_pk_add_f32 v[46:47], v[46:47], v[52:53]
	v_fmamk_f32 v45, v21, 0xba800000, v45
	v_fmac_f32_e32 v44, 0xba800000, v21
	v_fmamk_f32 v43, v21, 0xba800000, v43
	v_fmac_f32_e32 v42, 0xba800000, v21
	v_pk_fma_f32 v[50:51], v[38:39], v[38:39], v[54:55] op_sel_hi:[1,1,0]
	v_pk_fma_f32 v[54:55], v[40:41], v[40:41], v[56:57] op_sel_hi:[1,1,0]
	v_pk_add_f32 v[48:49], v[48:49], v[48:49] op_sel_hi:[0,1]
	v_pk_add_f32 v[46:47], v[46:47], v[46:47] op_sel_hi:[0,1]
	v_mul_f32_e32 v50, v42, v42
	v_mul_f32_e32 v54, v43, v43
	v_mul_f32_e32 v48, v44, v44
	v_mul_f32_e32 v46, v45, v45
	v_pk_add_f32 v[50:51], v[50:51], v[54:55]
	v_pk_add_f32 v[46:47], v[48:49], v[46:47]
	s_nop 0
	v_pk_add_f32 v[46:47], v[50:51], v[46:47]
	v_mov_b32_e32 v51, 0
	v_add_f32_e32 v21, v46, v47
	ds_bpermute_b32 v46, v12, v21
	s_waitcnt lgkmcnt(0)
	v_add_f32_e32 v21, v21, v46
	ds_bpermute_b32 v46, v13, v21
	s_waitcnt lgkmcnt(0)
	v_add_f32_e32 v21, v21, v46
	ds_bpermute_b32 v46, v14, v21
	s_waitcnt lgkmcnt(0)
	v_add_f32_e32 v21, v21, v46
	ds_bpermute_b32 v46, v15, v21
	s_waitcnt lgkmcnt(0)
	v_add_f32_e32 v21, v21, v46
	ds_bpermute_b32 v46, v16, v21
	s_waitcnt lgkmcnt(0)
	v_add_f32_e32 v21, v21, v46
	ds_bpermute_b32 v46, v17, v21
	s_waitcnt lgkmcnt(0)
	v_add_f32_e32 v21, v21, v46
	v_fmamk_f32 v21, v21, 0x3a800000, v18
	v_mul_f32_e32 v46, 0x4f800000, v21
	v_cmp_gt_f32_e32 vcc, s3, v21
	s_nop 1
	v_cndmask_b32_e32 v21, v21, v46, vcc
	v_sqrt_f32_e32 v46, v21
	s_nop 0
	v_add_u32_e32 v47, -1, v46
	v_add_u32_e32 v48, 1, v46
	v_fma_f32 v49, -v47, v46, v21
	v_fma_f32 v50, -v48, v46, v21
	v_cmp_ge_f32_e64 s[0:1], 0, v49
	s_nop 1
	v_cndmask_b32_e64 v46, v46, v47, s[0:1]
	v_cmp_lt_f32_e64 s[0:1], 0, v50
	s_nop 1
	v_cndmask_b32_e64 v46, v46, v48, s[0:1]
	v_mul_f32_e32 v47, 0x37800000, v46
	v_cndmask_b32_e32 v46, v46, v47, vcc
	v_cmp_class_f32_e32 vcc, v21, v19
	s_nop 1
	v_cndmask_b32_e32 v21, v46, v21, vcc
	v_div_scale_f32 v46, s[0:1], v21, v21, 1.0
	v_rcp_f32_e32 v48, v46
	v_div_scale_f32 v47, vcc, 1.0, v21, 1.0
	v_fma_f32 v49, -v46, v48, 1.0
	v_fmac_f32_e32 v48, v49, v48
	v_mul_f32_e32 v49, v47, v48
	v_fma_f32 v50, -v46, v49, v47
	v_fmac_f32_e32 v49, v50, v48
	v_fma_f32 v46, -v46, v49, v47
	v_div_fmas_f32 v46, v46, v48, v49
	v_div_fixup_f32 v46, v46, v21, 1.0
	v_pk_mul_f32 v[30:31], v[30:31], v[46:47] op_sel_hi:[1,0]
	v_pk_mul_f32 v[32:33], v[32:33], v[46:47] op_sel_hi:[1,0]
	v_pk_fma_f32 v[22:23], v[22:23], v[30:31], v[26:27]
	v_pk_fma_f32 v[24:25], v[24:25], v[32:33], v[28:29]
	global_store_dwordx4 v[10:11], v[22:25], off
	global_load_dwordx4 v[26:29], v[0:1], off offset:1024
	global_load_dwordx4 v[30:33], v[2:3], off offset:1024
	v_pk_mul_f32 v[34:35], v[34:35], v[46:47] op_sel_hi:[1,0]
	v_pk_mul_f32 v[36:37], v[36:37], v[46:47] op_sel_hi:[1,0]
	v_pk_mul_f32 v[38:39], v[38:39], v[46:47] op_sel_hi:[1,0]
	v_pk_mul_f32 v[40:41], v[40:41], v[46:47] op_sel_hi:[1,0]
	v_mov_b32_e32 v21, 0
	v_med3_f32 v22, v22, s12, v20
	v_med3_f32 v23, v23, s12, v20
	v_mov_b32_e32 v47, 0
	v_cvt_pk_fp8_f32 v21, v22, v23
	v_mov_b32_e32 v50, 0
	v_pk_mul_f32 v[42:43], v[42:43], v[46:47] op_sel_hi:[1,0]
	v_pk_mul_f32 v[44:45], v[44:45], v[46:47] op_sel_hi:[1,0]
	v_med3_f32 v24, v24, s12, v20
	v_med3_f32 v25, v25, s12, v20
	v_cvt_pk_fp8_f32 v21, v24, v25 op_sel:[0,0,1]
	v_lshl_add_u64 v[48:49], s[84:85], 0, v[4:5]
	v_add_co_u32_e32 v48, vcc, s13, v48
	v_lshl_add_u64 v[4:5], v[4:5], 0, s[4:5]
	s_nop 0
	v_addc_co_u32_e32 v49, vcc, 0, v49, vcc
	s_waitcnt vmcnt(0)
	v_pk_fma_f32 v[28:29], v[28:29], v[36:37], v[32:33]
	v_pk_fma_f32 v[26:27], v[26:27], v[34:35], v[30:31]
	global_store_dwordx4 v[10:11], v[26:29], off offset:1024
	global_load_dwordx4 v[30:33], v[0:1], off offset:2048
	global_load_dwordx4 v[34:37], v[2:3], off offset:2048
	v_med3_f32 v22, v26, s12, v20
	v_med3_f32 v23, v27, s12, v20
	v_cvt_pk_fp8_f32 v47, v22, v23
	v_med3_f32 v24, v28, s12, v20
	v_med3_f32 v25, v29, s12, v20
	v_cvt_pk_fp8_f32 v47, v24, v25 op_sel:[0,0,1]
	s_waitcnt vmcnt(0)
	v_pk_fma_f32 v[32:33], v[32:33], v[40:41], v[36:37]
	v_pk_fma_f32 v[30:31], v[30:31], v[38:39], v[34:35]
	global_store_dwordx4 v[10:11], v[30:33], off offset:2048
	global_load_dwordx4 v[34:37], v[0:1], off offset:3072
	global_load_dwordx4 v[38:41], v[2:3], off offset:3072
	v_med3_f32 v22, v30, s12, v20
	v_med3_f32 v23, v31, s12, v20
	v_cvt_pk_fp8_f32 v50, v22, v23
	v_med3_f32 v24, v32, s12, v20
	v_med3_f32 v25, v33, s12, v20
	v_cvt_pk_fp8_f32 v50, v24, v25 op_sel:[0,0,1]
	s_waitcnt vmcnt(0)
	v_pk_fma_f32 v[22:23], v[34:35], v[42:43], v[38:39]
	s_nop 0
	v_med3_f32 v26, v22, s12, v20
	v_med3_f32 v27, v23, s12, v20
	v_cvt_pk_fp8_f32 v51, v26, v27
	v_pk_fma_f32 v[24:25], v[36:37], v[44:45], v[40:41]
	global_store_dwordx4 v[10:11], v[22:25], off offset:3072
	v_med3_f32 v10, v24, s12, v20
	v_med3_f32 v11, v25, s12, v20
	v_cvt_pk_fp8_f32 v51, v10, v11 op_sel:[0,0,1]
	global_store_dword v[48:49], v21, off
	global_store_dword v[48:49], v47, off offset:256
	global_store_dword v[48:49], v50, off offset:512
	global_store_dword v[48:49], v51, off offset:768
	s_cbranch_scc1 .LBB0_521
	v_readlane_b32 s81, v234, 49

.LBB0_724:
	v_lshl_add_u64 v[26:27], s[84:85], 0, v[4:5]
	v_add_co_u32_e32 v28, vcc, 0x14400000, v26
	v_lshl_add_u64 v[24:25], s[84:85], 0, v[6:7]
	s_nop 0
	v_addc_co_u32_e32 v29, vcc, 0, v27, vcc
	v_add_co_u32_e32 v42, vcc, 0x10400000, v24
	global_load_dwordx4 v[16:19], v[0:1], off
	global_load_dwordx4 v[20:23], v[2:3], off
	v_add_co_u32_e64 v40, s[0:1], s9, v26
	global_load_dwordx2 v[44:45], v[28:29], off nt
	global_load_dwordx2 v[46:47], v[28:29], off offset:512 nt
	global_load_dwordx2 v[48:49], v[28:29], off offset:1024 nt
	global_load_dwordx2 v[50:51], v[28:29], off offset:1536 nt
	v_addc_co_u32_e32 v43, vcc, 0, v25, vcc
	v_addc_co_u32_e64 v41, s[0:1], 0, v27, s[0:1]
	global_load_dwordx4 v[24:27], v[42:43], off nt
	global_load_dwordx4 v[28:31], v[42:43], off offset:1024 nt
	global_load_dwordx4 v[32:35], v[42:43], off offset:2048 nt
	global_load_dwordx4 v[36:39], v[42:43], off offset:3072 nt
	s_add_i32 s10, s10, s80
	v_lshl_add_u64 v[4:5], v[4:5], 0, s[4:5]
	v_lshl_add_u64 v[6:7], v[6:7], 0, s[6:7]
	s_cmpk_lt_i32 s10, 0x4000
	s_waitcnt vmcnt(7)
	v_lshlrev_b32_e32 v52, 16, v44
	v_and_b32_e32 v53, 0xffff0000, v44
	v_lshlrev_b32_e32 v44, 16, v45
	v_and_b32_e32 v45, 0xffff0000, v45
	s_waitcnt vmcnt(6)
	v_lshlrev_b32_e32 v54, 16, v46
	v_and_b32_e32 v55, 0xffff0000, v46
	v_lshlrev_b32_e32 v46, 16, v47
	v_and_b32_e32 v47, 0xffff0000, v47
	s_waitcnt vmcnt(5)
	v_lshlrev_b32_e32 v56, 16, v48
	v_and_b32_e32 v57, 0xffff0000, v48
	v_lshlrev_b32_e32 v48, 16, v49
	v_and_b32_e32 v49, 0xffff0000, v49
	s_waitcnt vmcnt(4)
	v_lshlrev_b32_e32 v58, 16, v50
	v_and_b32_e32 v59, 0xffff0000, v50
	v_lshlrev_b32_e32 v50, 16, v51
	v_and_b32_e32 v51, 0xffff0000, v51
	s_waitcnt vmcnt(3)
	v_pk_fma_f32 v[26:27], v[26:27], s[8:9], v[44:45] op_sel_hi:[1,0,1]
	v_pk_fma_f32 v[24:25], v[24:25], s[8:9], v[52:53] op_sel_hi:[1,0,1]
	s_waitcnt vmcnt(2)
	v_pk_fma_f32 v[30:31], v[30:31], s[8:9], v[46:47] op_sel_hi:[1,0,1]
	v_pk_fma_f32 v[28:29], v[28:29], s[8:9], v[54:55] op_sel_hi:[1,0,1]
	s_waitcnt vmcnt(1)
	v_pk_fma_f32 v[34:35], v[34:35], s[8:9], v[48:49] op_sel_hi:[1,0,1]
	s_waitcnt vmcnt(0)
	v_pk_fma_f32 v[38:39], v[38:39], s[8:9], v[50:51] op_sel_hi:[1,0,1]
	v_pk_mov_b32 v[44:45], v[24:25], v[26:27] op_sel:[1,0]
	v_mov_b32_e32 v46, v24
	v_mov_b32_e32 v47, v27
	v_pk_mov_b32 v[48:49], v[28:29], v[30:31] op_sel:[1,0]
	v_mov_b32_e32 v50, v28
	v_mov_b32_e32 v51, v31
	v_pk_add_f32 v[44:45], v[44:45], v[46:47]
	v_pk_add_f32 v[46:47], v[48:49], v[50:51]
	v_pk_fma_f32 v[32:33], v[32:33], s[8:9], v[56:57] op_sel_hi:[1,0,1]
	v_pk_fma_f32 v[36:37], v[36:37], s[8:9], v[58:59] op_sel_hi:[1,0,1]
	v_add_f32_e32 v50, v44, v45
	v_pk_add_f32 v[44:45], v[46:47], v[46:47] op_sel:[0,1] op_sel_hi:[1,0]
	v_add_f32_e32 v52, v32, v33
	v_add_f32_e32 v54, v34, v35
	v_mov_b32_e32 v57, v36
	v_mov_b32_e32 v53, v38
	v_mov_b32_e32 v55, v39
	v_add_f32_e32 v56, 0, v50
	v_mov_b32_e32 v45, v37
	v_pk_add_f32 v[48:49], v[52:53], v[54:55]
	v_pk_add_f32 v[44:45], v[56:57], v[44:45]
	s_nop 0
	v_pk_add_f32 v[44:45], v[44:45], v[48:49]
	s_nop 0
	v_add_f32_e32 v44, v44, v45
	ds_bpermute_b32 v45, v8, v44
	s_waitcnt lgkmcnt(0)
	v_add_f32_e32 v44, v44, v45
	ds_bpermute_b32 v45, v9, v44
	s_waitcnt lgkmcnt(0)
	v_add_f32_e32 v44, v44, v45
	ds_bpermute_b32 v45, v10, v44
	s_waitcnt lgkmcnt(0)
	v_add_f32_e32 v44, v44, v45
	ds_bpermute_b32 v45, v11, v44
	s_waitcnt lgkmcnt(0)
	v_add_f32_e32 v44, v44, v45
	ds_bpermute_b32 v45, v12, v44
	s_waitcnt lgkmcnt(0)
	v_add_f32_e32 v44, v44, v45
	ds_bpermute_b32 v45, v13, v44
	s_waitcnt lgkmcnt(0)
	v_add_f32_e32 v44, v44, v45
	v_fmamk_f32 v25, v44, 0xba800000, v25
	v_fmac_f32_e32 v24, 0xba800000, v44
	v_fmamk_f32 v27, v44, 0xba800000, v27
	v_fmac_f32_e32 v26, 0xba800000, v44
	v_fmamk_f32 v29, v44, 0xba800000, v29
	v_fmac_f32_e32 v28, 0xba800000, v44
	v_fmamk_f32 v31, v44, 0xba800000, v31
	v_fmac_f32_e32 v30, 0xba800000, v44
	v_fmamk_f32 v33, v44, 0xba800000, v33
	v_fmac_f32_e32 v32, 0xba800000, v44
	v_fmamk_f32 v35, v44, 0xba800000, v35
	v_fmac_f32_e32 v34, 0xba800000, v44
	v_fmamk_f32 v39, v44, 0xba800000, v39
	v_fmac_f32_e32 v38, 0xba800000, v44
	v_fmamk_f32 v37, v44, 0xba800000, v37
	v_fmac_f32_e32 v36, 0xba800000, v44
	v_pk_mul_f32 v[44:45], v[26:27], v[26:27]
	v_pk_mul_f32 v[46:47], v[24:25], v[24:25]
	v_pk_mul_f32 v[48:49], v[30:31], v[30:31]
	v_pk_mul_f32 v[50:51], v[28:29], v[28:29]
	v_pk_mov_b32 v[56:57], v[46:47], v[44:45] op_sel:[1,0]
	v_mov_b32_e32 v47, v45
	v_pk_mov_b32 v[44:45], v[50:51], v[48:49] op_sel:[1,0]
	v_mov_b32_e32 v51, v49
	v_mul_f32_e32 v52, v32, v32
	v_mul_f32_e32 v54, v34, v34
	v_pk_add_f32 v[46:47], v[56:57], v[46:47]
	v_pk_add_f32 v[44:45], v[44:45], v[50:51]
	v_pk_fma_f32 v[48:49], v[32:33], v[32:33], v[52:53] op_sel_hi:[1,1,0]
	v_pk_fma_f32 v[52:53], v[34:35], v[34:35], v[54:55] op_sel_hi:[1,1,0]
	v_pk_add_f32 v[46:47], v[46:47], v[46:47] op_sel_hi:[0,1]
	v_pk_add_f32 v[44:45], v[44:45], v[44:45] op_sel_hi:[0,1]
	v_mul_f32_e32 v48, v36, v36
	v_mul_f32_e32 v52, v37, v37
	v_mul_f32_e32 v46, v38, v38
	v_mul_f32_e32 v44, v39, v39
	v_pk_add_f32 v[48:49], v[48:49], v[52:53]
	v_pk_add_f32 v[44:45], v[46:47], v[44:45]
	s_nop 0
	v_pk_add_f32 v[44:45], v[48:49], v[44:45]
	s_nop 0
	v_add_f32_e32 v44, v44, v45
	ds_bpermute_b32 v45, v8, v44
	s_waitcnt lgkmcnt(0)
	v_add_f32_e32 v44, v44, v45
	ds_bpermute_b32 v45, v9, v44
	s_waitcnt lgkmcnt(0)
	v_add_f32_e32 v44, v44, v45
	ds_bpermute_b32 v45, v10, v44
	s_waitcnt lgkmcnt(0)
	v_add_f32_e32 v44, v44, v45
	ds_bpermute_b32 v45, v11, v44
	s_waitcnt lgkmcnt(0)
	v_add_f32_e32 v44, v44, v45
	ds_bpermute_b32 v45, v12, v44
	s_waitcnt lgkmcnt(0)
	v_add_f32_e32 v44, v44, v45
	ds_bpermute_b32 v45, v13, v44
	s_waitcnt lgkmcnt(0)
	v_add_f32_e32 v44, v44, v45
	v_fmamk_f32 v44, v44, 0x3a800000, v14
	v_mul_f32_e32 v45, 0x4f800000, v44
	v_cmp_gt_f32_e32 vcc, s3, v44
	s_nop 1
	v_cndmask_b32_e32 v44, v44, v45, vcc
	v_sqrt_f32_e32 v45, v44
	s_nop 0
	v_add_u32_e32 v46, -1, v45
	v_add_u32_e32 v47, 1, v45
	v_fma_f32 v48, -v46, v45, v44
	v_fma_f32 v49, -v47, v45, v44
	v_cmp_ge_f32_e64 s[0:1], 0, v48
	s_nop 1
	v_cndmask_b32_e64 v45, v45, v46, s[0:1]
	v_cmp_lt_f32_e64 s[0:1], 0, v49
	s_nop 1
	v_cndmask_b32_e64 v45, v45, v47, s[0:1]
	v_mul_f32_e32 v46, 0x37800000, v45
	v_cndmask_b32_e32 v45, v45, v46, vcc
	v_cmp_class_f32_e32 vcc, v44, v15
	s_nop 1
	v_cndmask_b32_e32 v44, v45, v44, vcc
	v_div_scale_f32 v45, s[0:1], v44, v44, 1.0
	v_rcp_f32_e32 v47, v45
	v_div_scale_f32 v46, vcc, 1.0, v44, 1.0
	v_fma_f32 v48, -v45, v47, 1.0
	v_fmac_f32_e32 v47, v48, v47
	v_mul_f32_e32 v48, v46, v47
	v_fma_f32 v49, -v45, v48, v46
	v_fmac_f32_e32 v48, v49, v47
	v_fma_f32 v45, -v45, v48, v46
	v_div_fmas_f32 v45, v45, v47, v48
	v_div_fixup_f32 v44, v45, v44, 1.0
	v_pk_mul_f32 v[24:25], v[24:25], v[44:45] op_sel_hi:[1,0]
	v_pk_mul_f32 v[26:27], v[26:27], v[44:45] op_sel_hi:[1,0]
	v_pk_fma_f32 v[16:17], v[16:17], v[24:25], v[20:21]
	v_pk_fma_f32 v[18:19], v[18:19], v[26:27], v[22:23]
	global_store_dwordx4 v[42:43], v[16:19], off
	v_pk_mul_f32 v[24:25], v[30:31], v[44:45] op_sel_hi:[1,0]
	v_pk_mul_f32 v[26:27], v[28:29], v[44:45] op_sel_hi:[1,0]
	v_cvt_pk_bf16_f32 v16, v16, v17
	v_cvt_pk_bf16_f32 v17, v18, v19
	global_store_dwordx2 v[40:41], v[16:17], off
	global_load_dwordx4 v[16:19], v[0:1], off offset:1024
	s_nop 0
	global_load_dwordx4 v[20:23], v[2:3], off offset:1024
	s_waitcnt vmcnt(0)
	v_pk_fma_f32 v[16:17], v[16:17], v[26:27], v[20:21]
	v_pk_fma_f32 v[18:19], v[18:19], v[24:25], v[22:23]
	global_store_dwordx4 v[42:43], v[16:19], off offset:1024
	v_pk_mul_f32 v[24:25], v[34:35], v[44:45] op_sel_hi:[1,0]
	v_pk_mul_f32 v[26:27], v[32:33], v[44:45] op_sel_hi:[1,0]
	v_cvt_pk_bf16_f32 v16, v16, v17
	v_cvt_pk_bf16_f32 v17, v18, v19
	global_store_dwordx2 v[40:41], v[16:17], off offset:512
	global_load_dwordx4 v[16:19], v[0:1], off offset:2048
	s_nop 0
	global_load_dwordx4 v[20:23], v[2:3], off offset:2048
	s_waitcnt vmcnt(0)
	v_pk_fma_f32 v[16:17], v[16:17], v[26:27], v[20:21]
	v_pk_fma_f32 v[18:19], v[18:19], v[24:25], v[22:23]
	global_store_dwordx4 v[42:43], v[16:19], off offset:2048
	v_pk_mul_f32 v[24:25], v[38:39], v[44:45] op_sel_hi:[1,0]
	v_pk_mul_f32 v[26:27], v[36:37], v[44:45] op_sel_hi:[1,0]
	v_cvt_pk_bf16_f32 v16, v16, v17
	v_cvt_pk_bf16_f32 v17, v18, v19
	global_store_dwordx2 v[40:41], v[16:17], off offset:1024
	global_load_dwordx4 v[16:19], v[0:1], off offset:3072
	s_nop 0
	global_load_dwordx4 v[20:23], v[2:3], off offset:3072
	s_waitcnt vmcnt(0)
	v_pk_fma_f32 v[16:17], v[16:17], v[26:27], v[20:21]
	v_pk_fma_f32 v[18:19], v[18:19], v[24:25], v[22:23]
	global_store_dwordx4 v[42:43], v[16:19], off offset:3072
	s_nop 1
	v_cvt_pk_bf16_f32 v16, v16, v17
	v_cvt_pk_bf16_f32 v17, v18, v19
	global_store_dwordx2 v[40:41], v[16:17], off offset:1536
	s_cbranch_scc1 .LBB0_724
	v_readlane_b32 s81, v234, 49

.LBB0_1060:
	v_lshl_add_u64 v[0:1], s[84:85], 0, v[24:25]
	v_add_co_u32_e32 v0, vcc, 0x14400000, v0
	s_waitcnt lgkmcnt(6)
	v_lshl_add_u64 v[2:3], s[84:85], 0, v[22:23]
	v_addc_co_u32_e32 v1, vcc, 0, v1, vcc
	global_load_dwordx2 v[4:5], v[0:1], off nt
	s_waitcnt lgkmcnt(0)
	global_load_dwordx2 v[14:15], v[0:1], off offset:512 nt
	global_load_dwordx2 v[28:29], v[0:1], off offset:1024 nt
	v_add_co_u32_e32 v26, vcc, 0x10400000, v2
	global_load_dwordx2 v[30:31], v[0:1], off offset:1536 nt
	s_nop 0
	v_addc_co_u32_e32 v27, vcc, 0, v3, vcc
	global_load_dwordx4 v[0:3], v[26:27], off nt
	global_load_dwordx4 v[6:9], v[26:27], off offset:1024 nt
	global_load_dwordx4 v[10:13], v[26:27], off offset:2048 nt
	global_load_dwordx4 v[56:59], v[26:27], off offset:3072 nt
	s_waitcnt vmcnt(7)
	v_lshlrev_b32_e32 v32, 16, v4
	v_and_b32_e32 v33, 0xffff0000, v4
	v_lshlrev_b32_e32 v4, 16, v5
	v_and_b32_e32 v5, 0xffff0000, v5
	s_waitcnt vmcnt(6)
	v_lshlrev_b32_e32 v34, 16, v14
	v_and_b32_e32 v35, 0xffff0000, v14
	v_lshlrev_b32_e32 v14, 16, v15
	v_and_b32_e32 v15, 0xffff0000, v15
	s_waitcnt vmcnt(5)
	v_lshlrev_b32_e32 v38, 16, v28
	v_and_b32_e32 v39, 0xffff0000, v28
	v_lshlrev_b32_e32 v28, 16, v29
	v_and_b32_e32 v29, 0xffff0000, v29
	s_waitcnt vmcnt(3)
	v_pk_fma_f32 v[4:5], v[2:3], s[30:31], v[4:5] op_sel_hi:[1,0,1]
	v_pk_fma_f32 v[64:65], v[0:1], s[30:31], v[32:33] op_sel_hi:[1,0,1]
	s_waitcnt vmcnt(2)
	v_pk_fma_f32 v[0:1], v[8:9], s[30:31], v[14:15] op_sel_hi:[1,0,1]
	v_pk_fma_f32 v[2:3], v[6:7], s[30:31], v[34:35] op_sel_hi:[1,0,1]
	v_lshlrev_b32_e32 v60, 16, v30
	v_and_b32_e32 v61, 0xffff0000, v30
	v_lshlrev_b32_e32 v62, 16, v31
	v_and_b32_e32 v63, 0xffff0000, v31
	s_waitcnt vmcnt(1)
	v_pk_fma_f32 v[28:29], v[12:13], s[30:31], v[28:29] op_sel_hi:[1,0,1]
	v_pk_fma_f32 v[30:31], v[10:11], s[30:31], v[38:39] op_sel_hi:[1,0,1]
	v_pk_mov_b32 v[6:7], v[64:65], v[4:5] op_sel:[1,0]
	v_mov_b32_e32 v8, v64
	v_mov_b32_e32 v9, v5
	v_pk_mov_b32 v[10:11], v[2:3], v[0:1] op_sel:[1,0]
	v_mov_b32_e32 v12, v2
	v_mov_b32_e32 v13, v1
	v_pk_add_f32 v[6:7], v[6:7], v[8:9]
	v_pk_add_f32 v[8:9], v[10:11], v[12:13]
	s_waitcnt vmcnt(0)
	v_pk_fma_f32 v[32:33], v[58:59], s[30:31], v[62:63] op_sel_hi:[1,0,1]
	v_pk_fma_f32 v[34:35], v[56:57], s[30:31], v[60:61] op_sel_hi:[1,0,1]
	v_add_f32_e32 v12, v6, v7
	v_pk_add_f32 v[6:7], v[8:9], v[8:9] op_sel:[0,1] op_sel_hi:[1,0]
	v_add_f32_e32 v14, v30, v31
	v_add_f32_e32 v38, v28, v29
	v_mov_b32_e32 v57, v34
	v_mov_b32_e32 v15, v32
	v_mov_b32_e32 v39, v33
	v_add_f32_e32 v56, 0, v12
	v_mov_b32_e32 v7, v35
	v_pk_add_f32 v[10:11], v[14:15], v[38:39]
	v_pk_add_f32 v[6:7], v[56:57], v[6:7]
	s_nop 0
	v_pk_add_f32 v[6:7], v[6:7], v[10:11]
	global_load_dwordx4 v[8:11], v[16:17], off
	global_load_dwordx4 v[12:15], v[18:19], off
	v_add_f32_e32 v6, v6, v7
	ds_bpermute_b32 v7, v40, v6
	s_waitcnt lgkmcnt(0)
	v_add_f32_e32 v6, v6, v7
	ds_bpermute_b32 v7, v41, v6
	s_waitcnt lgkmcnt(0)
	v_add_f32_e32 v6, v6, v7
	ds_bpermute_b32 v7, v42, v6
	s_waitcnt lgkmcnt(0)
	v_add_f32_e32 v6, v6, v7
	ds_bpermute_b32 v7, v43, v6
	s_waitcnt lgkmcnt(0)
	v_add_f32_e32 v6, v6, v7
	ds_bpermute_b32 v7, v44, v6
	s_waitcnt lgkmcnt(0)
	v_add_f32_e32 v6, v6, v7
	ds_bpermute_b32 v7, v45, v6
	s_waitcnt lgkmcnt(0)
	v_add_f32_e32 v6, v6, v7
	v_fmamk_f32 v65, v6, 0xba800000, v65
	v_fmac_f32_e32 v64, 0xba800000, v6
	v_fmamk_f32 v5, v6, 0xba800000, v5
	v_fmac_f32_e32 v4, 0xba800000, v6
	v_fmamk_f32 v3, v6, 0xba800000, v3
	v_fmac_f32_e32 v2, 0xba800000, v6
	v_fmamk_f32 v1, v6, 0xba800000, v1
	v_fmac_f32_e32 v0, 0xba800000, v6
	v_fmamk_f32 v31, v6, 0xba800000, v31
	v_fmac_f32_e32 v30, 0xba800000, v6
	v_fmamk_f32 v29, v6, 0xba800000, v29
	v_fmac_f32_e32 v28, 0xba800000, v6
	v_fmamk_f32 v33, v6, 0xba800000, v33
	v_fmac_f32_e32 v32, 0xba800000, v6
	v_fmamk_f32 v35, v6, 0xba800000, v35
	v_fmac_f32_e32 v34, 0xba800000, v6
	v_pk_mul_f32 v[6:7], v[4:5], v[4:5]
	v_pk_mul_f32 v[38:39], v[64:65], v[64:65]
	v_pk_mul_f32 v[56:57], v[0:1], v[0:1]
	v_pk_mul_f32 v[58:59], v[2:3], v[2:3]
	v_pk_mov_b32 v[62:63], v[38:39], v[6:7] op_sel:[1,0]
	v_mov_b32_e32 v39, v7
	v_pk_mov_b32 v[6:7], v[58:59], v[56:57] op_sel:[1,0]
	v_mov_b32_e32 v59, v57
	v_mul_f32_e32 v36, v30, v30
	v_mul_f32_e32 v60, v28, v28
	v_pk_add_f32 v[38:39], v[62:63], v[38:39]
	v_pk_add_f32 v[6:7], v[6:7], v[58:59]
	v_pk_fma_f32 v[56:57], v[30:31], v[30:31], v[36:37] op_sel_hi:[1,1,0]
	v_pk_fma_f32 v[60:61], v[28:29], v[28:29], v[60:61] op_sel_hi:[1,1,0]
	v_pk_add_f32 v[38:39], v[38:39], v[38:39] op_sel_hi:[0,1]
	v_pk_add_f32 v[6:7], v[6:7], v[6:7] op_sel_hi:[0,1]
	v_mul_f32_e32 v56, v34, v34
	v_mul_f32_e32 v60, v35, v35
	v_mul_f32_e32 v38, v32, v32
	v_mul_f32_e32 v6, v33, v33
	v_pk_add_f32 v[56:57], v[56:57], v[60:61]
	v_pk_add_f32 v[6:7], v[38:39], v[6:7]
	v_mov_b32_e32 v58, 0
	v_pk_add_f32 v[6:7], v[56:57], v[6:7]
	v_mov_b32_e32 v57, 0
	v_add_f32_e32 v6, v6, v7
	ds_bpermute_b32 v7, v40, v6
	v_mov_b32_e32 v56, 0
	s_waitcnt lgkmcnt(0)
	v_add_f32_e32 v6, v6, v7
	ds_bpermute_b32 v7, v41, v6
	s_waitcnt lgkmcnt(0)
	v_add_f32_e32 v6, v6, v7
	ds_bpermute_b32 v7, v42, v6
	s_waitcnt lgkmcnt(0)
	v_add_f32_e32 v6, v6, v7
	ds_bpermute_b32 v7, v43, v6
	s_waitcnt lgkmcnt(0)
	v_add_f32_e32 v6, v6, v7
	ds_bpermute_b32 v7, v44, v6
	s_waitcnt lgkmcnt(0)
	v_add_f32_e32 v6, v6, v7
	ds_bpermute_b32 v7, v45, v6
	s_waitcnt lgkmcnt(0)
	v_add_f32_e32 v6, v6, v7
	v_fmamk_f32 v6, v6, 0x3a800000, v48
	v_mul_f32_e32 v7, 0x4f800000, v6
	v_cmp_gt_f32_e32 vcc, s23, v6
	s_nop 1
	v_cndmask_b32_e32 v6, v6, v7, vcc
	v_sqrt_f32_e32 v7, v6
	s_nop 0
	v_add_u32_e32 v36, -1, v7
	v_add_u32_e32 v38, 1, v7
	v_fma_f32 v39, -v36, v7, v6
	v_fma_f32 v55, -v38, v7, v6
	v_cmp_ge_f32_e64 s[6:7], 0, v39
	s_nop 1
	v_cndmask_b32_e64 v7, v7, v36, s[6:7]
	v_cmp_lt_f32_e64 s[6:7], 0, v55
	s_nop 1
	v_cndmask_b32_e64 v7, v7, v38, s[6:7]
	v_mul_f32_e32 v36, 0x37800000, v7
	v_cndmask_b32_e32 v7, v7, v36, vcc
	v_cmp_class_f32_e32 vcc, v6, v49
	s_nop 1
	v_cndmask_b32_e32 v6, v7, v6, vcc
	v_div_scale_f32 v7, s[6:7], v6, v6, 1.0
	v_rcp_f32_e32 v36, v7
	v_div_scale_f32 v38, vcc, 1.0, v6, 1.0
	v_fma_f32 v39, -v7, v36, 1.0
	v_fmac_f32_e32 v36, v39, v36
	v_mul_f32_e32 v39, v38, v36
	v_fma_f32 v55, -v7, v39, v38
	v_fmac_f32_e32 v39, v55, v36
	v_fma_f32 v7, -v7, v39, v38
	v_div_fmas_f32 v7, v7, v36, v39
	v_div_fixup_f32 v36, v7, v6, 1.0
	v_pk_mul_f32 v[38:39], v[64:65], v[36:37] op_sel_hi:[1,0]
	v_pk_mul_f32 v[4:5], v[4:5], v[36:37] op_sel_hi:[1,0]
	v_pk_mul_f32 v[0:1], v[0:1], v[36:37] op_sel_hi:[1,0]
	s_waitcnt vmcnt(0)
	v_pk_fma_f32 v[6:7], v[10:11], v[4:5], v[14:15]
	v_pk_fma_f32 v[4:5], v[8:9], v[38:39], v[12:13]
	global_store_dwordx4 v[26:27], v[4:7], off
	global_load_dwordx4 v[8:11], v[16:17], off offset:1024
	global_load_dwordx4 v[12:15], v[18:19], off offset:1024
	v_pk_mul_f32 v[38:39], v[2:3], v[36:37] op_sel_hi:[1,0]
	v_pk_mul_f32 v[30:31], v[30:31], v[36:37] op_sel_hi:[1,0]
	v_pk_mul_f32 v[28:29], v[28:29], v[36:37] op_sel_hi:[1,0]
	v_pk_mul_f32 v[34:35], v[34:35], v[36:37] op_sel_hi:[1,0]
	v_pk_mul_f32 v[32:33], v[32:33], v[36:37] op_sel_hi:[1,0]
	v_med3_f32 v36, v4, s31, v50
	v_med3_f32 v59, v5, s31, v50
	v_med3_f32 v187, v6, s31, v50
	v_med3_f32 v196, v7, s31, v50
	v_mov_b32_e32 v55, 0
	v_cvt_pk_fp8_f32 v55, v36, v59
	v_cvt_pk_fp8_f32 v55, v187, v196 op_sel:[0,0,1]
	s_waitcnt vmcnt(0)
	v_pk_fma_f32 v[2:3], v[10:11], v[0:1], v[14:15]
	v_pk_fma_f32 v[0:1], v[8:9], v[38:39], v[12:13]
	global_store_dwordx4 v[26:27], v[0:3], off offset:1024
	global_load_dwordx4 v[8:11], v[16:17], off offset:2048
	global_load_dwordx4 v[12:15], v[18:19], off offset:2048
	ds_read_b128 v[60:63], v51
	ds_read_b128 v[64:67], v51 offset:16
	ds_read_b128 v[68:71], v51 offset:32
	ds_read_b128 v[72:75], v51 offset:48
	ds_read_b128 v[76:79], v51 offset:64
	ds_read_b128 v[80:83], v51 offset:80
	ds_read_b128 v[84:87], v51 offset:96
	ds_read_b128 v[88:91], v51 offset:112
	ds_read_b128 v[92:95], v51 offset:8192
	ds_read_b128 v[96:99], v51 offset:8208
	ds_read_b128 v[100:103], v51 offset:8224
	ds_read_b128 v[104:107], v51 offset:8240
	ds_read_b128 v[108:111], v51 offset:8256
	ds_read_b128 v[112:115], v51 offset:8272
	ds_read_b128 v[116:119], v51 offset:8288
	ds_read_b128 v[120:123], v51 offset:8304
	ds_read_b128 v[124:127], v51 offset:16384
	ds_read_b128 v[128:131], v51 offset:16400
	ds_read_b128 v[132:135], v51 offset:16416
	ds_read_b128 v[136:139], v51 offset:16432
	ds_read_b128 v[140:143], v51 offset:16448
	ds_read_b128 v[144:147], v51 offset:16464
	ds_read_b128 v[148:151], v51 offset:16480
	ds_read_b128 v[152:155], v51 offset:16496
	ds_read_b128 v[156:159], v51 offset:24576
	ds_read_b128 v[164:167], v51 offset:24592
	ds_read_b128 v[168:171], v51 offset:24608
	ds_read_b128 v[172:175], v51 offset:24624
	ds_read_b128 v[176:179], v51 offset:24640
	ds_read_b128 v[180:183], v51 offset:24656
	ds_read_b128 v[188:191], v51 offset:24672
	ds_read_b128 v[192:195], v51 offset:24688
	s_waitcnt lgkmcnt(14)
	v_fma_f32 v62, v62, v4, 0
	v_fma_f32 v63, v63, v4, 0
	v_fma_f32 v64, v64, v4, 0
	v_fma_f32 v65, v65, v4, 0
	v_fma_f32 v66, v66, v4, 0
	v_fma_f32 v67, v67, v4, 0
	v_pk_fma_f32 v[60:61], v[60:61], v[4:5], 0 op_sel_hi:[1,0,0]
	v_fmac_f32_e32 v62, v70, v5
	v_fmac_f32_e32 v63, v71, v5
	v_fmac_f32_e32 v64, v72, v5
	v_fmac_f32_e32 v65, v73, v5
	v_fmac_f32_e32 v66, v74, v5
	v_fmac_f32_e32 v67, v75, v5
	v_pk_fma_f32 v[4:5], v[68:69], v[4:5], v[60:61] op_sel:[0,1,0]
	v_fmac_f32_e32 v62, v78, v6
	v_fmac_f32_e32 v63, v79, v6
	v_fmac_f32_e32 v64, v80, v6
	v_fmac_f32_e32 v65, v81, v6
	v_fmac_f32_e32 v66, v82, v6
	v_fmac_f32_e32 v67, v83, v6
	v_pk_fma_f32 v[4:5], v[76:77], v[6:7], v[4:5] op_sel_hi:[1,0,1]
	v_fmac_f32_e32 v62, v7, v86
	v_fmac_f32_e32 v63, v7, v87
	v_fmac_f32_e32 v64, v7, v88
	v_fmac_f32_e32 v65, v7, v89
	v_fmac_f32_e32 v66, v7, v90
	v_fmac_f32_e32 v67, v7, v91
	v_pk_fma_f32 v[4:5], v[6:7], v[84:85], v[4:5] op_sel:[1,0,0]
	v_fmac_f32_e32 v62, v0, v94
	v_fmac_f32_e32 v63, v0, v95
	v_fmac_f32_e32 v64, v0, v96
	v_fmac_f32_e32 v65, v0, v97
	v_fmac_f32_e32 v66, v0, v98
	v_fmac_f32_e32 v67, v0, v99
	v_pk_fma_f32 v[4:5], v[0:1], v[92:93], v[4:5] op_sel_hi:[0,1,1]
	v_med3_f32 v6, v0, s31, v50
	v_med3_f32 v7, v1, s31, v50
	v_fmac_f32_e32 v62, v1, v102
	v_fmac_f32_e32 v63, v1, v103
	v_fmac_f32_e32 v64, v1, v104
	v_fmac_f32_e32 v65, v1, v105
	v_fmac_f32_e32 v66, v1, v106
	v_fmac_f32_e32 v67, v1, v107
	v_pk_fma_f32 v[0:1], v[0:1], v[100:101], v[4:5] op_sel:[1,0,0]
	v_fmac_f32_e32 v62, v2, v110
	v_fmac_f32_e32 v63, v2, v111
	v_fmac_f32_e32 v64, v2, v112
	v_fmac_f32_e32 v65, v2, v113
	v_fmac_f32_e32 v66, v2, v114
	v_fmac_f32_e32 v67, v2, v115
	v_pk_fma_f32 v[0:1], v[2:3], v[108:109], v[0:1] op_sel_hi:[0,1,1]
	v_fmac_f32_e32 v62, v3, v118
	v_fmac_f32_e32 v63, v3, v119
	v_fmac_f32_e32 v64, v3, v120
	v_fmac_f32_e32 v65, v3, v121
	v_fmac_f32_e32 v66, v3, v122
	v_fmac_f32_e32 v67, v3, v123
	v_pk_fma_f32 v[0:1], v[2:3], v[116:117], v[0:1] op_sel:[1,0,0]
	v_med3_f32 v36, v2, s31, v50
	v_med3_f32 v59, v3, s31, v50
	v_cvt_pk_fp8_f32 v56, v6, v7
	v_lshl_add_u64 v[38:39], s[84:85], 0, v[20:21]
	v_add_co_u32_e32 v38, vcc, s36, v38
	v_cvt_pk_fp8_f32 v56, v36, v59 op_sel:[0,0,1]
	s_nop 0
	v_addc_co_u32_e32 v39, vcc, 0, v39, vcc
	s_waitcnt vmcnt(0)
	v_pk_fma_f32 v[10:11], v[10:11], v[28:29], v[14:15]
	v_pk_fma_f32 v[8:9], v[8:9], v[30:31], v[12:13]
	global_store_dwordx4 v[26:27], v[8:11], off offset:2048
	global_load_dwordx4 v[12:15], v[16:17], off offset:3072
	global_load_dwordx4 v[28:31], v[18:19], off offset:3072
	v_med3_f32 v2, v8, s31, v50
	v_med3_f32 v3, v9, s31, v50
	v_fmac_f32_e32 v62, v8, v126
	v_fmac_f32_e32 v63, v8, v127
	v_fmac_f32_e32 v64, v8, v128
	v_fmac_f32_e32 v65, v8, v129
	v_fmac_f32_e32 v66, v8, v130
	v_fmac_f32_e32 v67, v8, v131
	v_pk_fma_f32 v[0:1], v[8:9], v[124:125], v[0:1] op_sel_hi:[0,1,1]
	v_cvt_pk_fp8_f32 v57, v2, v3
	s_waitcnt lgkmcnt(13)
	v_pk_fma_f32 v[0:1], v[8:9], v[132:133], v[0:1] op_sel:[1,0,0]
	v_fmac_f32_e32 v62, v9, v134
	v_fmac_f32_e32 v63, v9, v135
	s_waitcnt lgkmcnt(12)
	v_fmac_f32_e32 v64, v9, v136
	v_fmac_f32_e32 v65, v9, v137
	v_fmac_f32_e32 v66, v9, v138
	v_fmac_f32_e32 v67, v9, v139
	s_waitcnt lgkmcnt(11)
	v_fmac_f32_e32 v62, v10, v142
	v_fmac_f32_e32 v63, v10, v143
	s_waitcnt lgkmcnt(10)
	v_fmac_f32_e32 v64, v10, v144
	v_fmac_f32_e32 v65, v10, v145
	v_fmac_f32_e32 v66, v10, v146
	v_fmac_f32_e32 v67, v10, v147
	v_pk_fma_f32 v[0:1], v[10:11], v[140:141], v[0:1] op_sel_hi:[0,1,1]
	s_waitcnt lgkmcnt(9)
	v_fmac_f32_e32 v62, v11, v150
	v_fmac_f32_e32 v63, v11, v151
	s_waitcnt lgkmcnt(8)
	v_fmac_f32_e32 v64, v11, v152
	v_fmac_f32_e32 v65, v11, v153
	v_fmac_f32_e32 v66, v11, v154
	v_fmac_f32_e32 v67, v11, v155
	v_pk_fma_f32 v[4:5], v[10:11], v[148:149], v[0:1] op_sel:[1,0,0]
	v_med3_f32 v6, v10, s31, v50
	v_med3_f32 v7, v11, s31, v50
	v_cvt_pk_fp8_f32 v57, v6, v7 op_sel:[0,0,1]
	s_waitcnt vmcnt(0)
	v_pk_fma_f32 v[0:1], v[12:13], v[34:35], v[28:29]
	v_pk_fma_f32 v[2:3], v[14:15], v[32:33], v[30:31]
	s_waitcnt lgkmcnt(7)
	v_fmac_f32_e32 v62, v0, v158
	v_fmac_f32_e32 v63, v0, v159
	s_waitcnt lgkmcnt(6)
	v_fmac_f32_e32 v64, v0, v164
	v_fmac_f32_e32 v65, v0, v165
	v_fmac_f32_e32 v66, v0, v166
	v_fmac_f32_e32 v67, v0, v167
	v_pk_fma_f32 v[4:5], v[0:1], v[156:157], v[4:5] op_sel_hi:[0,1,1]
	global_store_dwordx4 v[26:27], v[0:3], off offset:3072
	v_med3_f32 v6, v0, s31, v50
	v_med3_f32 v7, v1, s31, v50
	s_waitcnt lgkmcnt(5)
	v_fmac_f32_e32 v62, v1, v170
	v_fmac_f32_e32 v63, v1, v171
	s_waitcnt lgkmcnt(4)
	v_fmac_f32_e32 v64, v1, v172
	v_fmac_f32_e32 v65, v1, v173
	v_fmac_f32_e32 v66, v1, v174
	v_fmac_f32_e32 v67, v1, v175
	v_pk_fma_f32 v[0:1], v[0:1], v[168:169], v[4:5] op_sel:[1,0,0]
	s_waitcnt lgkmcnt(3)
	v_fmac_f32_e32 v62, v2, v178
	v_fmac_f32_e32 v63, v2, v179
	s_waitcnt lgkmcnt(2)
	v_fmac_f32_e32 v64, v2, v180
	v_fmac_f32_e32 v65, v2, v181
	v_fmac_f32_e32 v66, v2, v182
	v_fmac_f32_e32 v67, v2, v183
	v_pk_fma_f32 v[0:1], v[2:3], v[176:177], v[0:1] op_sel_hi:[0,1,1]
	s_waitcnt lgkmcnt(1)
	v_fmac_f32_e32 v62, v3, v190
	v_fmac_f32_e32 v63, v3, v191
	s_waitcnt lgkmcnt(0)
	v_fmac_f32_e32 v64, v3, v192
	v_fmac_f32_e32 v65, v3, v193
	v_fmac_f32_e32 v66, v3, v194
	v_fmac_f32_e32 v67, v3, v195
	v_pk_fma_f32 v[0:1], v[2:3], v[188:189], v[0:1] op_sel:[1,0,0]
	v_med3_f32 v8, v2, s31, v50
	v_med3_f32 v9, v3, s31, v50
	v_cvt_pk_fp8_f32 v58, v6, v7
	ds_bpermute_b32 v2, v40, v0
	ds_bpermute_b32 v3, v40, v1
	ds_bpermute_b32 v4, v40, v62
	ds_bpermute_b32 v5, v40, v63
	ds_bpermute_b32 v6, v40, v64
	ds_bpermute_b32 v7, v40, v65
	ds_bpermute_b32 v10, v40, v66
	ds_bpermute_b32 v11, v40, v67
	v_cvt_pk_fp8_f32 v58, v8, v9 op_sel:[0,0,1]
	s_waitcnt lgkmcnt(6)
	v_pk_add_f32 v[0:1], v[0:1], v[2:3]
	s_waitcnt lgkmcnt(5)
	v_add_f32_e32 v4, v62, v4
	s_waitcnt lgkmcnt(4)
	v_add_f32_e32 v5, v63, v5
	s_waitcnt lgkmcnt(3)
	v_add_f32_e32 v6, v64, v6
	s_waitcnt lgkmcnt(2)
	v_add_f32_e32 v7, v65, v7
	s_waitcnt lgkmcnt(1)
	v_add_f32_e32 v8, v66, v10
	s_waitcnt lgkmcnt(0)
	v_add_f32_e32 v9, v67, v11
	ds_bpermute_b32 v2, v41, v0
	ds_bpermute_b32 v3, v41, v1
	ds_bpermute_b32 v10, v41, v4
	ds_bpermute_b32 v11, v41, v5
	ds_bpermute_b32 v12, v41, v6
	ds_bpermute_b32 v13, v41, v7
	ds_bpermute_b32 v14, v41, v8
	ds_bpermute_b32 v15, v41, v9
	s_waitcnt lgkmcnt(6)
	v_pk_add_f32 v[0:1], v[0:1], v[2:3]
	s_waitcnt lgkmcnt(5)
	v_add_f32_e32 v4, v4, v10
	s_waitcnt lgkmcnt(4)
	v_add_f32_e32 v5, v5, v11
	s_waitcnt lgkmcnt(3)
	v_add_f32_e32 v6, v6, v12
	s_waitcnt lgkmcnt(2)
	v_add_f32_e32 v7, v7, v13
	s_waitcnt lgkmcnt(1)
	v_add_f32_e32 v8, v8, v14
	s_waitcnt lgkmcnt(0)
	v_add_f32_e32 v9, v9, v15
	ds_bpermute_b32 v2, v42, v0
	ds_bpermute_b32 v3, v42, v1
	ds_bpermute_b32 v10, v42, v4
	ds_bpermute_b32 v11, v42, v5
	ds_bpermute_b32 v12, v42, v6
	ds_bpermute_b32 v13, v42, v7
	ds_bpermute_b32 v14, v42, v8
	ds_bpermute_b32 v15, v42, v9
	s_waitcnt lgkmcnt(6)
	v_pk_add_f32 v[0:1], v[0:1], v[2:3]
	s_waitcnt lgkmcnt(5)
	v_add_f32_e32 v4, v4, v10
	s_waitcnt lgkmcnt(4)
	v_add_f32_e32 v5, v5, v11
	s_waitcnt lgkmcnt(3)
	v_add_f32_e32 v6, v6, v12
	s_waitcnt lgkmcnt(2)
	v_add_f32_e32 v7, v7, v13
	s_waitcnt lgkmcnt(1)
	v_add_f32_e32 v8, v8, v14
	s_waitcnt lgkmcnt(0)
	v_add_f32_e32 v9, v9, v15
	ds_bpermute_b32 v2, v43, v0
	ds_bpermute_b32 v3, v43, v1
	ds_bpermute_b32 v10, v43, v4
	ds_bpermute_b32 v11, v43, v5
	ds_bpermute_b32 v12, v43, v6
	ds_bpermute_b32 v13, v43, v7
	ds_bpermute_b32 v14, v43, v8
	ds_bpermute_b32 v15, v43, v9
	s_waitcnt lgkmcnt(6)
	v_pk_add_f32 v[0:1], v[0:1], v[2:3]
	s_waitcnt lgkmcnt(5)
	v_add_f32_e32 v4, v4, v10
	s_waitcnt lgkmcnt(4)
	v_add_f32_e32 v5, v5, v11
	s_waitcnt lgkmcnt(3)
	v_add_f32_e32 v6, v6, v12
	s_waitcnt lgkmcnt(2)
	v_add_f32_e32 v7, v7, v13
	s_waitcnt lgkmcnt(1)
	v_add_f32_e32 v8, v8, v14
	s_waitcnt lgkmcnt(0)
	v_add_f32_e32 v10, v9, v15
	ds_bpermute_b32 v2, v44, v0
	ds_bpermute_b32 v3, v44, v1
	ds_bpermute_b32 v9, v44, v4
	ds_bpermute_b32 v11, v44, v5
	ds_bpermute_b32 v12, v44, v6
	ds_bpermute_b32 v13, v44, v7
	ds_bpermute_b32 v14, v44, v8
	ds_bpermute_b32 v15, v44, v10
	s_waitcnt lgkmcnt(6)
	v_pk_add_f32 v[0:1], v[0:1], v[2:3]
	s_waitcnt lgkmcnt(5)
	v_add_f32_e32 v4, v4, v9
	s_waitcnt lgkmcnt(4)
	v_add_f32_e32 v5, v5, v11
	s_waitcnt lgkmcnt(3)
	v_add_f32_e32 v6, v6, v12
	s_waitcnt lgkmcnt(2)
	v_add_f32_e32 v7, v7, v13
	s_waitcnt lgkmcnt(1)
	v_add_f32_e32 v9, v8, v14
	s_waitcnt lgkmcnt(0)
	v_add_f32_e32 v11, v10, v15
	ds_bpermute_b32 v2, v45, v0
	ds_bpermute_b32 v3, v45, v1
	ds_bpermute_b32 v8, v45, v4
	ds_bpermute_b32 v10, v45, v5
	ds_bpermute_b32 v12, v45, v6
	ds_bpermute_b32 v13, v45, v7
	ds_bpermute_b32 v14, v45, v9
	ds_bpermute_b32 v15, v45, v11
	global_store_dword v[38:39], v55, off
	global_store_dword v[38:39], v56, off offset:256
	global_store_dword v[38:39], v57, off offset:512
	global_store_dword v[38:39], v58, off offset:768
	s_and_saveexec_b64 s[34:35], s[4:5]
	s_cbranch_execz .LBB0_1059
	s_waitcnt lgkmcnt(6)
	v_pk_add_f32 v[2:3], v[0:1], v[2:3]
	s_waitcnt lgkmcnt(5)
	v_add_f32_e32 v4, v4, v8
	v_cmp_gt_f32_e32 vcc, v3, v2
	s_waitcnt lgkmcnt(4)
	v_add_f32_e32 v5, v5, v10
	s_waitcnt lgkmcnt(3)
	v_add_f32_e32 v6, v6, v12
	v_cndmask_b32_e32 v0, v2, v3, vcc
	v_cmp_gt_f32_e64 s[6:7], v4, v0
	s_waitcnt lgkmcnt(2)
	v_add_f32_e32 v7, v7, v13
	s_waitcnt lgkmcnt(1)
	v_add_f32_e32 v9, v9, v14
	v_cndmask_b32_e64 v0, v0, v4, s[6:7]
	v_cmp_gt_f32_e64 s[8:9], v5, v0
	s_waitcnt lgkmcnt(0)
	v_add_f32_e32 v11, v11, v15
	v_cmp_lt_f32_e64 s[18:19], s37, v2
	v_cndmask_b32_e64 v0, v0, v5, s[8:9]
	v_cmp_gt_f32_e64 s[10:11], v6, v0
	s_ashr_i32 s21, s20, 31
	s_nop 0
	v_cndmask_b32_e64 v0, v0, v6, s[10:11]
	v_cmp_gt_f32_e64 s[12:13], v7, v0
	s_nop 1
	v_cndmask_b32_e64 v0, v0, v7, s[12:13]
	v_cmp_gt_f32_e64 s[14:15], v9, v0
	s_nop 1
	v_cndmask_b32_e64 v1, v0, v9, s[14:15]
	v_cndmask_b32_e64 v0, 0, 1, vcc
	v_cndmask_b32_e64 v0, v0, 2, s[6:7]
	v_cndmask_b32_e64 v0, v0, 3, s[8:9]
	v_cndmask_b32_e64 v0, v0, 4, s[10:11]
	v_cndmask_b32_e64 v0, v0, 5, s[12:13]
	v_cndmask_b32_e64 v0, v0, 6, s[14:15]
	v_cmp_ngt_f32_e32 vcc, v11, v1
	s_and_b64 s[42:43], s[14:15], vcc
	s_nop 0
	v_cndmask_b32_e32 v0, 7, v0, vcc
	v_cmp_ne_u32_e64 s[16:17], 0, v0
	s_and_b64 s[16:17], s[16:17], s[18:19]
	v_cmp_ne_u32_e64 s[14:15], 1, v0
	v_cndmask_b32_e64 v2, v53, v2, s[16:17]
	v_cmp_gt_f32_e64 s[16:17], v3, v2
	s_and_b64 s[14:15], s[14:15], s[16:17]
	v_cndmask_b32_e64 v2, v2, v3, s[14:15]
	v_cmp_ne_u32_e64 s[12:13], 2, v0
	v_cmp_gt_f32_e64 s[16:17], v4, v2
	s_and_b64 s[12:13], s[12:13], s[16:17]
	v_cndmask_b32_e64 v2, v2, v4, s[12:13]
	v_cmp_ne_u32_e64 s[10:11], 3, v0
	v_cmp_gt_f32_e64 s[16:17], v5, v2
	s_and_b64 s[10:11], s[10:11], s[16:17]
	v_cndmask_b32_e64 v2, v2, v5, s[10:11]
	v_cmp_ne_u32_e64 s[8:9], 4, v0
	v_cmp_gt_f32_e64 s[16:17], v6, v2
	s_and_b64 s[8:9], s[8:9], s[16:17]
	v_cndmask_b32_e64 v2, v2, v6, s[8:9]
	v_cmp_ne_u32_e64 s[6:7], 5, v0
	v_cmp_gt_f32_e64 s[16:17], v7, v2
	s_and_b64 s[6:7], s[6:7], s[16:17]
	v_cndmask_b32_e64 v2, v2, v7, s[6:7]
	v_cmp_ngt_f32_e64 s[16:17], v9, v2
	s_or_b64 s[16:17], s[42:43], s[16:17]
	v_cndmask_b32_e32 v1, v11, v1, vcc
	v_cndmask_b32_e64 v2, v9, v2, s[16:17]
	v_cmp_gt_f32_e64 s[18:19], v11, v2
	s_and_b64 s[18:19], vcc, s[18:19]
	v_cndmask_b32_e64 v3, 0, 1, s[14:15]
	v_cndmask_b32_e64 v2, v2, v11, s[18:19]
	v_sub_f32_e32 v4, v2, v1
	v_mul_f32_e32 v1, 0x3fb8aa3b, v4
	v_fma_f32 v2, v4, s38, -v1
	v_rndne_f32_e32 v5, v1
	v_fmac_f32_e32 v2, 0x32a5705f, v4
	v_sub_f32_e32 v1, v1, v5
	v_add_f32_e32 v1, v1, v2
	v_cndmask_b32_e64 v3, v3, 2, s[12:13]
	v_exp_f32_e32 v1, v1
	v_cvt_i32_f32_e32 v5, v5
	v_cndmask_b32_e64 v3, v3, 3, s[10:11]
	v_cndmask_b32_e64 v3, v3, 4, s[8:9]
	v_cndmask_b32_e64 v2, v3, 5, s[6:7]
	v_cndmask_b32_e64 v2, 6, v2, s[16:17]
	v_ldexp_f32 v1, v1, v5
	v_cmp_ngt_f32_e32 vcc, s39, v4
	v_cndmask_b32_e64 v2, v2, 7, s[18:19]
	v_lshl_add_u32 v3, v2, 2, 0
	v_cndmask_b32_e32 v5, 0, v1, vcc
	v_lshl_add_u32 v1, v0, 2, 0
	ds_add_rtn_u32 v1, v1, v52 offset:32768
	ds_add_rtn_u32 v3, v3, v52 offset:32768
	v_cmp_nlt_f32_e32 vcc, s40, v4
	s_and_b32 s6, s3, 60
	v_lshl_add_u32 v6, s6, 2, v46
	v_cndmask_b32_e32 v4, v54, v5, vcc
	v_add_f32_e32 v5, 1.0, v4
	s_waitcnt lgkmcnt(0)
	ds_write_b128 v6, v[0:3] offset:32832
	v_div_scale_f32 v0, s[6:7], v5, v5, v4
	v_rcp_f32_e32 v1, v0
	s_lshl_b64 s[6:7], s[20:21], 2
	s_add_u32 s6, s54, s6
	s_addc_u32 s7, s55, s7
	v_fma_f32 v2, -v0, v1, 1.0
	v_fmac_f32_e32 v1, v2, v1
	v_div_scale_f32 v2, vcc, v4, v5, v4
	v_mul_f32_e32 v3, v2, v1
	v_fma_f32 v6, -v0, v3, v2
	v_fmac_f32_e32 v3, v6, v1
	v_fma_f32 v0, -v0, v3, v2
	v_div_scale_f32 v2, s[8:9], v5, v5, 1.0
	v_rcp_f32_e32 v6, v2
	v_div_fmas_f32 v0, v0, v1, v3
	v_div_fixup_f32 v1, v0, v5, v4
	v_fma_f32 v0, -v2, v6, 1.0
	v_fmac_f32_e32 v6, v0, v6
	v_div_scale_f32 v0, vcc, 1.0, v5, 1.0
	v_mul_f32_e32 v3, v0, v6
	v_fma_f32 v4, -v2, v3, v0
	v_fmac_f32_e32 v3, v4, v6
	v_fma_f32 v0, -v2, v3, v0
	v_div_fmas_f32 v0, v0, v6, v3
	v_div_fixup_f32 v0, v0, v5, 1.0
	global_store_dwordx2 v47, v[0:1], s[6:7]
	s_branch .LBB0_1059

.LBB0_1411:
	s_ashr_i32 s3, s2, 31
	v_lshl_add_u64 v[8:9], s[8:9], 0, v[2:3]
	s_lshl_b64 s[0:1], s[2:3], 2
	v_add_co_u32_e32 v8, vcc, s12, v8
	s_add_u32 s14, s50, s0
	s_nop 0
	v_addc_co_u32_e32 v9, vcc, 0, v9, vcc
	s_addc_u32 s15, s51, s1
	global_load_dwordx4 v[22:25], v[4:5], off
	global_load_dwordx4 v[26:29], v[6:7], off
	global_load_dwordx4 v[30:33], v[8:9], off nt
	global_load_dwordx4 v[34:37], v[8:9], off offset:1024 nt
	global_load_dwordx4 v[38:41], v[8:9], off offset:2048 nt
	global_load_dwordx4 v[42:45], v[8:9], off offset:3072 nt
	s_add_u32 s0, s54, s0
	global_load_dwordx2 v[8:9], v18, s[14:15]
	s_addc_u32 s1, s55, s1
	global_load_dwordx2 v[46:47], v18, s[0:1]
	v_lshl_add_u64 v[10:11], s[4:5], 0, v[2:3]
	s_add_i32 s46, s46, s80
	s_add_i32 s2, s2, s11
	s_add_u32 s4, s4, s6
	s_addc_u32 s5, s5, s7
	s_add_u32 s8, s8, s6
	s_addc_u32 s9, s9, s7
	s_cmpk_lt_i32 s46, 0x4000
	s_waitcnt vmcnt(1)
	v_ashrrev_i32_e32 v49, 31, v8
	v_mov_b32_e32 v48, v8
	v_ashrrev_i32_e32 v51, 31, v9
	v_mov_b32_e32 v50, v9
	v_lshlrev_b64 v[8:9], 11, v[48:49]
	v_lshlrev_b64 v[48:49], 11, v[50:51]
	v_lshl_add_u64 v[8:9], v[0:1], 0, v[8:9]
	v_lshl_add_u64 v[48:49], v[0:1], 0, v[48:49]
	global_load_dwordx2 v[50:51], v[8:9], off nt
	global_load_dwordx2 v[52:53], v[48:49], off nt
	global_load_dwordx2 v[54:55], v[8:9], off offset:512 nt
	global_load_dwordx2 v[56:57], v[48:49], off offset:512 nt
	global_load_dwordx2 v[58:59], v[8:9], off offset:1024 nt
	global_load_dwordx2 v[60:61], v[48:49], off offset:1024 nt
	global_load_dwordx2 v[62:63], v[8:9], off offset:1536 nt
	global_load_dwordx2 v[64:65], v[48:49], off offset:1536 nt
	s_waitcnt vmcnt(7)
	v_lshlrev_b32_e32 v8, 16, v50
	v_and_b32_e32 v9, 0xffff0000, v50
	v_lshlrev_b32_e32 v48, 16, v51
	v_and_b32_e32 v49, 0xffff0000, v51
	s_waitcnt vmcnt(6)
	v_lshlrev_b32_e32 v50, 16, v52
	v_and_b32_e32 v51, 0xffff0000, v52
	v_lshlrev_b32_e32 v52, 16, v53
	v_and_b32_e32 v53, 0xffff0000, v53
	s_waitcnt vmcnt(4)
	v_lshlrev_b32_e32 v68, 16, v56
	v_and_b32_e32 v69, 0xffff0000, v56
	v_lshlrev_b32_e32 v56, 16, v57
	v_and_b32_e32 v57, 0xffff0000, v57
	v_lshlrev_b32_e32 v66, 16, v54
	v_and_b32_e32 v67, 0xffff0000, v54
	v_lshlrev_b32_e32 v54, 16, v55
	v_and_b32_e32 v55, 0xffff0000, v55
	s_waitcnt vmcnt(2)
	v_lshlrev_b32_e32 v72, 16, v60
	v_and_b32_e32 v73, 0xffff0000, v60
	v_lshlrev_b32_e32 v60, 16, v61
	v_and_b32_e32 v61, 0xffff0000, v61
	s_waitcnt vmcnt(0)
	v_lshlrev_b32_e32 v76, 16, v64
	v_and_b32_e32 v77, 0xffff0000, v64
	v_lshlrev_b32_e32 v64, 16, v65
	v_and_b32_e32 v65, 0xffff0000, v65
	v_pk_mul_f32 v[52:53], v[46:47], v[52:53] op_sel:[1,0]
	v_pk_mul_f32 v[50:51], v[46:47], v[50:51] op_sel:[1,0]
	v_pk_mul_f32 v[56:57], v[46:47], v[56:57] op_sel:[1,0]
	v_pk_mul_f32 v[68:69], v[46:47], v[68:69] op_sel:[1,0]
	v_lshlrev_b32_e32 v70, 16, v58
	v_and_b32_e32 v71, 0xffff0000, v58
	v_lshlrev_b32_e32 v58, 16, v59
	v_and_b32_e32 v59, 0xffff0000, v59
	v_lshlrev_b32_e32 v74, 16, v62
	v_and_b32_e32 v75, 0xffff0000, v62
	v_lshlrev_b32_e32 v62, 16, v63
	v_and_b32_e32 v63, 0xffff0000, v63
	v_pk_mul_f32 v[60:61], v[46:47], v[60:61] op_sel:[1,0]
	v_pk_mul_f32 v[72:73], v[46:47], v[72:73] op_sel:[1,0]
	v_pk_mul_f32 v[64:65], v[46:47], v[64:65] op_sel:[1,0]
	v_pk_mul_f32 v[76:77], v[46:47], v[76:77] op_sel:[1,0]
	v_pk_fma_f32 v[8:9], v[46:47], v[8:9], v[50:51] op_sel_hi:[0,1,1]
	v_pk_fma_f32 v[48:49], v[46:47], v[48:49], v[52:53] op_sel_hi:[0,1,1]
	v_pk_fma_f32 v[50:51], v[46:47], v[66:67], v[68:69] op_sel_hi:[0,1,1]
	v_pk_fma_f32 v[52:53], v[46:47], v[54:55], v[56:57] op_sel_hi:[0,1,1]
	v_pk_fma_f32 v[54:55], v[46:47], v[70:71], v[72:73] op_sel_hi:[0,1,1]
	v_pk_fma_f32 v[56:57], v[46:47], v[58:59], v[60:61] op_sel_hi:[0,1,1]
	v_pk_fma_f32 v[58:59], v[46:47], v[74:75], v[76:77] op_sel_hi:[0,1,1]
	v_pk_fma_f32 v[46:47], v[46:47], v[62:63], v[64:65] op_sel_hi:[0,1,1]
	v_pk_fma_f32 v[32:33], v[32:33], s[10:11], v[48:49] op_sel_hi:[1,0,1]
	v_pk_fma_f32 v[8:9], v[30:31], s[10:11], v[8:9] op_sel_hi:[1,0,1]
	v_pk_fma_f32 v[30:31], v[36:37], s[10:11], v[52:53] op_sel_hi:[1,0,1]
	v_pk_fma_f32 v[34:35], v[34:35], s[10:11], v[50:51] op_sel_hi:[1,0,1]
	v_pk_fma_f32 v[36:37], v[40:41], s[10:11], v[56:57] op_sel_hi:[1,0,1]
	v_pk_fma_f32 v[40:41], v[44:45], s[10:11], v[46:47] op_sel_hi:[1,0,1]
	v_pk_mov_b32 v[44:45], v[8:9], v[32:33] op_sel:[1,0]
	v_mov_b32_e32 v46, v8
	v_mov_b32_e32 v47, v33
	v_pk_mov_b32 v[48:49], v[34:35], v[30:31] op_sel:[1,0]
	v_mov_b32_e32 v50, v34
	v_mov_b32_e32 v51, v31
	v_pk_add_f32 v[44:45], v[44:45], v[46:47]
	v_pk_add_f32 v[46:47], v[48:49], v[50:51]
	v_pk_fma_f32 v[38:39], v[38:39], s[10:11], v[54:55] op_sel_hi:[1,0,1]
	v_pk_fma_f32 v[42:43], v[42:43], s[10:11], v[58:59] op_sel_hi:[1,0,1]
	v_add_f32_e32 v21, v44, v45
	v_pk_add_f32 v[44:45], v[46:47], v[46:47] op_sel:[0,1] op_sel_hi:[1,0]
	v_add_f32_e32 v52, v38, v39
	v_add_f32_e32 v54, v36, v37
	v_mov_b32_e32 v57, v42
	v_mov_b32_e32 v53, v40
	v_mov_b32_e32 v55, v41
	v_add_f32_e32 v56, 0, v21
	v_mov_b32_e32 v45, v43
	v_pk_add_f32 v[48:49], v[52:53], v[54:55]
	v_pk_add_f32 v[44:45], v[56:57], v[44:45]
	s_nop 0
	v_pk_add_f32 v[44:45], v[44:45], v[48:49]
	s_nop 0
	v_add_f32_e32 v21, v44, v45
	ds_bpermute_b32 v44, v12, v21
	s_waitcnt lgkmcnt(0)
	v_add_f32_e32 v21, v21, v44
	ds_bpermute_b32 v44, v13, v21
	s_waitcnt lgkmcnt(0)
	v_add_f32_e32 v21, v21, v44
	ds_bpermute_b32 v44, v14, v21
	s_waitcnt lgkmcnt(0)
	v_add_f32_e32 v21, v21, v44
	ds_bpermute_b32 v44, v15, v21
	s_waitcnt lgkmcnt(0)
	v_add_f32_e32 v21, v21, v44
	ds_bpermute_b32 v44, v16, v21
	s_waitcnt lgkmcnt(0)
	v_add_f32_e32 v21, v21, v44
	ds_bpermute_b32 v44, v17, v21
	s_waitcnt lgkmcnt(0)
	v_add_f32_e32 v21, v21, v44
	v_fmamk_f32 v9, v21, 0xba800000, v9
	v_fmac_f32_e32 v8, 0xba800000, v21
	v_fmamk_f32 v33, v21, 0xba800000, v33
	v_fmac_f32_e32 v32, 0xba800000, v21
	v_fmamk_f32 v35, v21, 0xba800000, v35
	v_fmac_f32_e32 v34, 0xba800000, v21
	v_fmamk_f32 v31, v21, 0xba800000, v31
	v_fmac_f32_e32 v30, 0xba800000, v21
	v_pk_mul_f32 v[44:45], v[32:33], v[32:33]
	v_pk_mul_f32 v[46:47], v[8:9], v[8:9]
	v_pk_mul_f32 v[48:49], v[30:31], v[30:31]
	v_pk_mul_f32 v[50:51], v[34:35], v[34:35]
	v_fmac_f32_e32 v38, 0xba800000, v21
	v_fmac_f32_e32 v36, 0xba800000, v21
	v_pk_mov_b32 v[56:57], v[46:47], v[44:45] op_sel:[1,0]
	v_mov_b32_e32 v47, v45
	v_pk_mov_b32 v[44:45], v[50:51], v[48:49] op_sel:[1,0]
	v_mov_b32_e32 v51, v49
	v_fmamk_f32 v39, v21, 0xba800000, v39
	v_fmamk_f32 v37, v21, 0xba800000, v37
	v_mul_f32_e32 v52, v38, v38
	v_mul_f32_e32 v54, v36, v36
	v_pk_add_f32 v[46:47], v[56:57], v[46:47]
	v_pk_add_f32 v[44:45], v[44:45], v[50:51]
	v_fmamk_f32 v41, v21, 0xba800000, v41
	v_fmac_f32_e32 v40, 0xba800000, v21
	v_fmamk_f32 v43, v21, 0xba800000, v43
	v_fmac_f32_e32 v42, 0xba800000, v21
	v_pk_fma_f32 v[48:49], v[38:39], v[38:39], v[52:53] op_sel_hi:[1,1,0]
	v_pk_fma_f32 v[52:53], v[36:37], v[36:37], v[54:55] op_sel_hi:[1,1,0]
	v_pk_add_f32 v[46:47], v[46:47], v[46:47] op_sel_hi:[0,1]
	v_pk_add_f32 v[44:45], v[44:45], v[44:45] op_sel_hi:[0,1]
	v_mul_f32_e32 v48, v42, v42
	v_mul_f32_e32 v52, v43, v43
	v_mul_f32_e32 v46, v40, v40
	v_mul_f32_e32 v44, v41, v41
	v_pk_add_f32 v[48:49], v[48:49], v[52:53]
	v_pk_add_f32 v[44:45], v[46:47], v[44:45]
	s_nop 0
	v_pk_add_f32 v[44:45], v[48:49], v[44:45]
	s_nop 0
	v_add_f32_e32 v21, v44, v45
	ds_bpermute_b32 v44, v12, v21
	s_waitcnt lgkmcnt(0)
	v_add_f32_e32 v21, v21, v44
	ds_bpermute_b32 v44, v13, v21
	s_waitcnt lgkmcnt(0)
	v_add_f32_e32 v21, v21, v44
	ds_bpermute_b32 v44, v14, v21
	s_waitcnt lgkmcnt(0)
	v_add_f32_e32 v21, v21, v44
	ds_bpermute_b32 v44, v15, v21
	s_waitcnt lgkmcnt(0)
	v_add_f32_e32 v21, v21, v44
	ds_bpermute_b32 v44, v16, v21
	s_waitcnt lgkmcnt(0)
	v_add_f32_e32 v21, v21, v44
	ds_bpermute_b32 v44, v17, v21
	s_waitcnt lgkmcnt(0)
	v_add_f32_e32 v21, v21, v44
	v_fmamk_f32 v21, v21, 0x3a800000, v19
	v_mul_f32_e32 v44, 0x4f800000, v21
	v_cmp_gt_f32_e32 vcc, s13, v21
	s_nop 1
	v_cndmask_b32_e32 v21, v21, v44, vcc
	v_sqrt_f32_e32 v44, v21
	s_nop 0
	v_add_u32_e32 v45, -1, v44
	v_add_u32_e32 v46, 1, v44
	v_fma_f32 v47, -v45, v44, v21
	v_fma_f32 v48, -v46, v44, v21
	v_cmp_ge_f32_e64 s[0:1], 0, v47
	s_nop 1
	v_cndmask_b32_e64 v44, v44, v45, s[0:1]
	v_cmp_lt_f32_e64 s[0:1], 0, v48
	s_nop 1
	v_cndmask_b32_e64 v44, v44, v46, s[0:1]
	v_mul_f32_e32 v45, 0x37800000, v44
	v_cndmask_b32_e32 v44, v44, v45, vcc
	v_cmp_class_f32_e32 vcc, v21, v20
	s_nop 1
	v_cndmask_b32_e32 v21, v44, v21, vcc
	v_div_scale_f32 v44, s[0:1], v21, v21, 1.0
	v_rcp_f32_e32 v46, v44
	v_div_scale_f32 v45, vcc, 1.0, v21, 1.0
	v_fma_f32 v47, -v44, v46, 1.0
	v_fmac_f32_e32 v46, v47, v46
	v_mul_f32_e32 v47, v45, v46
	v_fma_f32 v48, -v44, v47, v45
	v_fmac_f32_e32 v47, v48, v46
	v_fma_f32 v44, -v44, v47, v45
	v_div_fmas_f32 v44, v44, v46, v47
	v_div_fixup_f32 v44, v44, v21, 1.0
	v_pk_mul_f32 v[8:9], v[8:9], v[44:45] op_sel_hi:[1,0]
	v_pk_mul_f32 v[32:33], v[32:33], v[44:45] op_sel_hi:[1,0]
	v_pk_fma_f32 v[22:23], v[22:23], v[8:9], v[26:27]
	v_pk_fma_f32 v[24:25], v[24:25], v[32:33], v[28:29]
	global_store_dwordx4 v[10:11], v[22:25], off
	global_load_dwordx4 v[22:25], v[4:5], off offset:1024
	s_nop 0
	global_load_dwordx4 v[26:29], v[6:7], off offset:1024
	v_pk_mul_f32 v[8:9], v[30:31], v[44:45] op_sel_hi:[1,0]
	v_pk_mul_f32 v[30:31], v[34:35], v[44:45] op_sel_hi:[1,0]
	s_waitcnt vmcnt(0)
	v_pk_fma_f32 v[24:25], v[24:25], v[8:9], v[28:29]
	v_pk_fma_f32 v[22:23], v[22:23], v[30:31], v[26:27]
	global_store_dwordx4 v[10:11], v[22:25], off offset:1024
	global_load_dwordx4 v[22:25], v[4:5], off offset:2048
	s_nop 0
	global_load_dwordx4 v[26:29], v[6:7], off offset:2048
	v_pk_mul_f32 v[8:9], v[36:37], v[44:45] op_sel_hi:[1,0]
	v_pk_mul_f32 v[30:31], v[38:39], v[44:45] op_sel_hi:[1,0]
	s_waitcnt vmcnt(0)
	v_pk_fma_f32 v[24:25], v[24:25], v[8:9], v[28:29]
	v_pk_fma_f32 v[22:23], v[22:23], v[30:31], v[26:27]
	global_store_dwordx4 v[10:11], v[22:25], off offset:2048
	global_load_dwordx4 v[22:25], v[4:5], off offset:3072
	s_nop 0
	global_load_dwordx4 v[26:29], v[6:7], off offset:3072
	v_pk_mul_f32 v[8:9], v[40:41], v[44:45] op_sel_hi:[1,0]
	v_pk_mul_f32 v[30:31], v[42:43], v[44:45] op_sel_hi:[1,0]
	s_waitcnt vmcnt(0)
	v_pk_fma_f32 v[24:25], v[24:25], v[8:9], v[28:29]
	v_pk_fma_f32 v[22:23], v[22:23], v[30:31], v[26:27]
	global_store_dwordx4 v[10:11], v[22:25], off offset:3072
	s_cbranch_scc1 .LBB0_1411
